# TYPE0 attention: ALiBi bias folded into QK accumulator init (32 fmamk instead of 64 VALU per off-diagonal tile), static prio for waves 4-7 in attention, skip last grid barrier
# speedup vs baseline: 1.0232x; 1.0232x over previous
; __device__ __forceinline__ float wave_sum(float v) { return xor32_sum(xor16_sum(row16_sum(v))); }
; #define AIN(i) (kargs()->in[i])
; #define K_TID ((wave_s << 6) | lane_fresh())
; #define K_LANE (lane_fresh())
; __global__ void __launch_bounds__(512, 2) fwd_megakernel(Args a) {
;     ...
;             int lane_l = K_LANE, tid_l = K_TID; asm volatile("" : "+v"(lane_l), "+v"(tid_l));
;             const float* gq = AIN(4) + l * 6 * 64;
;             float mg[6];
; #pragma unroll
;             for (int j = 0; j < 6; ++j) mg[j] = wave_max(fabsf(gq[j * 64 + lane_l]));
;             const float* rel = AIN(8) + l * 6 * 257;
;             float mr = 0.f;
;             for (int i = lane_l; i < 6 * 257; i += 64) mr = fmaxf(mr, fabsf(rel[i]));
;             mr = wave_max(mr);
;             const float* lp = AIN(5) + l * 4 * 64;
;             const float s01 = wave_sum(lp[lane_l] * lp[64 + lane_l]), s23 = wave_sum(lp[128 + lane_l] * lp[192 + lane_l]);
.LBB0_345:
	s_or_b64 exec, exec, s[4:5]
	s_mov_b32 s1, -1
	s_waitcnt lgkmcnt(0)
	s_barrier
	s_cselect_b32 s98, 1, 0
	s_cmp_ge_u32 s82, 0x100
	s_cbranch_scc0 .Lprio_skip_1
	s_setprio 1
.Lprio_skip_1:
	s_cmp_lg_u32 s98, 0
	s_mov_b32 s0, -1
	v_mbcnt_lo_u32_b32 v0, s1, 0
	v_mbcnt_hi_u32_b32 v0, s1, v0
	s_mov_b64 s[2:3], s[46:47]
	v_mbcnt_lo_u32_b32 v1, s0, 0
	v_mbcnt_hi_u32_b32 v1, s0, v1
	s_mov_b64 s[0:1], s[46:47]
	v_or_b32_e32 v150, s82, v1
	s_load_dwordx2 s[0:1], s[0:1], 0x20
	v_ashrrev_i32_e32 v1, 31, v0
	v_lshlrev_b64 v[0:1], 2, v[0:1]
	v_mov_b32_e32 v8, 0
	v_mov_b32_e32 v12, 0
	s_waitcnt lgkmcnt(0)
	v_lshl_add_u64 v[2:3], s[0:1], 0, v[0:1]
	global_load_dword v4, v[2:3], off
	global_load_dword v5, v[2:3], off offset:256
	global_load_dword v6, v[2:3], off offset:512
	s_mov_b64 s[0:1], s[46:47]
	global_load_dword v2, v[2:3], off offset:768
	s_load_dwordx2 s[80:81], s[0:1], 0x40
	s_load_dwordx2 s[0:1], s[2:3], 0x28
	v_mov_b32_e32 v9, 0
	v_mov_b32_e32 v3, 0
	v_mov_b32_e32 v10, 0
	v_mov_b32_e32 v13, 0
	s_waitcnt lgkmcnt(0)
	v_lshl_add_u64 v[0:1], s[0:1], 0, v[0:1]
	global_load_dword v19, v[0:1], off
	global_load_dword v20, v[0:1], off offset:256
	global_load_dword v21, v[0:1], off offset:512
	global_load_dword v22, v[0:1], off offset:768
	v_mov_b32_e32 v16, 0
	v_mov_b32_e32 v11, 0
	v_mov_b32_e32 v14, 0
	v_mov_b32_e32 v17, 0
	v_mov_b32_e32 v15, 0
	v_mov_b32_e32 v18, 0
	v_mov_b32_e32 v7, 0
	s_mov_b64 s[0:1], s[46:47]
	s_mov_b32 s2, 0x3fb8aa3b
	s_load_dwordx2 s[0:1], s[0:1], 0x98
	s_waitcnt lgkmcnt(0)
	v_writelane_b32 v251, s0, 15
	s_nop 1
	v_writelane_b32 v251, s1, 16
	s_mov_b64 s[0:1], s[46:47]
	s_load_dwordx2 s[4:5], s[0:1], 0x98
	s_mov_b64 s[0:1], s[46:47]
	s_load_dwordx2 s[6:7], s[0:1], 0x98
	s_mov_b64 s[0:1], s[46:47]
	s_load_dwordx2 s[20:21], s[0:1], 0x30
	s_mov_b32 s0, 0xc2ce8ed0
	s_mov_b32 s1, 0x42b17218
	s_waitcnt vmcnt(7)
	v_and_b32_e32 v0, 0x7fffffff, v4
	s_nop 1
	v_mov_b32_dpp v8, v0 quad_perm:[1,0,3,2] row_mask:0xf bank_mask:0xf
	v_max_f32_e64 v1, |v4|, |v4|
	s_waitcnt vmcnt(6)
	v_and_b32_e32 v4, 0x7fffffff, v5
	v_max_f32_e32 v0, v8, v8
	v_max_f32_e32 v0, v1, v0
	v_mov_b32_dpp v12, v4 quad_perm:[1,0,3,2] row_mask:0xf bank_mask:0xf
	v_max_f32_e64 v5, |v5|, |v5|
	v_max_f32_e32 v4, v12, v12
	v_mov_b32_dpp v9, v0 quad_perm:[2,3,0,1] row_mask:0xf bank_mask:0xf
	s_waitcnt vmcnt(5)
	v_and_b32_e32 v23, 0x7fffffff, v6
	v_max_f32_e32 v1, v5, v4
	v_max_f32_e32 v4, v9, v9
	v_mov_b32_dpp v3, v23 quad_perm:[1,0,3,2] row_mask:0xf bank_mask:0xf
	v_max_f32_e32 v0, v0, v4
	v_max_f32_e64 v6, |v6|, |v6|
	v_max_f32_e32 v3, v3, v3
	v_mov_b32_dpp v10, v0 row_half_mirror row_mask:0xf bank_mask:0xf
	v_max_f32_e32 v3, v6, v3
	v_max_f32_e32 v4, v10, v10
	v_mov_b32_dpp v13, v1 quad_perm:[2,3,0,1] row_mask:0xf bank_mask:0xf
	v_mov_b32_dpp v16, v3 quad_perm:[2,3,0,1] row_mask:0xf bank_mask:0xf
	v_max_f32_e32 v0, v0, v4
	v_max_f32_e32 v5, v13, v13
	v_max_f32_e32 v6, v16, v16
	v_mov_b32_dpp v11, v0 row_mirror row_mask:0xf bank_mask:0xf
	v_max_f32_e32 v1, v1, v5
	v_max_f32_e32 v3, v3, v6
	v_max_f32_e32 v4, v11, v11
	v_mov_b32_dpp v14, v1 row_half_mirror row_mask:0xf bank_mask:0xf
	v_mov_b32_dpp v17, v3 row_half_mirror row_mask:0xf bank_mask:0xf
	v_max_f32_e32 v0, v0, v4
	v_max_f32_e32 v5, v14, v14
	v_max_f32_e32 v6, v17, v17
	v_mov_b32_e32 v4, v0
	v_max_f32_e32 v1, v1, v5
	v_max_f32_e32 v3, v3, v6
	v_permlane16_swap_b32_e32 v0, v4
	v_mov_b32_dpp v15, v1 row_mirror row_mask:0xf bank_mask:0xf
	v_mov_b32_dpp v18, v3 row_mirror row_mask:0xf bank_mask:0xf
	v_max_f32_e32 v4, v4, v4
	v_max_f32_e32 v0, v0, v0
	v_max_f32_e32 v5, v15, v15
	v_max_f32_e32 v6, v18, v18
	v_max_f32_e32 v0, v0, v4
	v_max_f32_e32 v1, v1, v5
	v_max_f32_e32 v3, v3, v6
	v_mov_b32_e32 v4, v0
	v_mov_b32_e32 v5, v1
	v_mov_b32_e32 v6, v3
	v_permlane32_swap_b32_e32 v0, v4
	v_permlane16_swap_b32_e32 v1, v5
	v_max_f32_e32 v4, v4, v4
	v_max_f32_e32 v0, v0, v0
	v_permlane16_swap_b32_e32 v3, v6
	v_max_f32_e32 v5, v5, v5
	v_max_f32_e32 v1, v1, v1
	v_max_f32_e32 v0, v0, v4
	v_max_f32_e32 v4, v6, v6
	v_max_f32_e32 v3, v3, v3
	v_max_f32_e32 v1, v1, v5
	v_max_f32_e32 v3, v3, v4
	v_mov_b32_e32 v5, v1
	v_mov_b32_e32 v4, v3
	s_nop 0
	v_permlane32_swap_b32_e32 v1, v5
	v_permlane32_swap_b32_e32 v3, v4
	v_max_f32_e32 v5, v5, v5
	v_max_f32_e32 v1, v1, v1
	v_max_f32_e32 v4, v4, v4
	v_max_f32_e32 v3, v3, v3
	v_max_f32_e32 v1, v1, v5
	v_max_f32_e32 v3, v3, v4
	s_waitcnt vmcnt(4)
; #define LAS __attribute__((address_space(3)))
; __device__ __forceinline__ float wave_sum(float v) { return xor32_sum(xor16_sum(row16_sum(v))); }
; #define AIN(i) (kargs()->in[i])
; #define AWS (kargs()->ws)
;             #define RFL(x) __uint_as_float(__builtin_amdgcn_readfirstlane(__float_as_uint(x)))
; __device__ __forceinline__ void attn_phase(const AttnCtx& C, unsigned* counter, LAS unsigned char* lds, int tid) {
;     LAS unsigned* ub = (LAS unsigned*)(lds + AL_U);
;     __syncthreads();
;     if (tid == 0) ub[0] = atomicAdd(counter, 1u);
; __global__ void __launch_bounds__(512, 2) fwd_megakernel(Args a) {
;     ...
;             for (int j = 0; j < 6; ++j) mg[j] = wave_max(fabsf(gq[j * 64 + lane_l]));
;             const float* rel = AIN(8) + l * 6 * 257;
;             float mr = 0.f;
;             for (int i = lane_l; i < 6 * 257; i += 64) mr = fmaxf(mr, fabsf(rel[i]));
;             mr = wave_max(mr);
;             const float* lp = AIN(5) + l * 4 * 64;
;             const float s01 = wave_sum(lp[lane_l] * lp[64 + lane_l]), s23 = wave_sum(lp[128 + lane_l] * lp[192 + lane_l]);
;             const float lam_init = (l == 0) ? 0.2f : (0.8f - 0.6f * 0.7408182206817179f);
;             AttnCtx C;
;             C.Z = P_Zb; C.O = P_HN; C.F2 = P_F2; C.rel = rel; C.subln = AIN(6) + l * 64;
;             C.lam = expf(s01) - expf(s23) + lam_init; C.oml = 1.0f - lam_init;
;             C.Mb0 = 8.0f * mg[0] * mg[1] * LOG2E * 1.02f + 1.0f; C.Mb1 = 8.0f * mg[2] * mg[3] * LOG2E * 1.02f + 1.0f; C.Mb2 = 8.0f * mg[4] * mg[5] * LOG2E * 1.02f + 1.0f + mr * LOG2E;
;     ...
;             C.lam = RFL(C.lam); C.oml = RFL(C.oml); C.Mb0 = RFL(C.Mb0); C.Mb1 = RFL(C.Mb1); C.Mb2 = RFL(C.Mb2);
;             attn_phase(C, (unsigned*)(AWS + WS_CTL) + CTL_Q + 16 * (1 + l), lds, tid_l);
	v_and_b32_e32 v4, 0x7fffffff, v2
	v_mov_b32_e32 v5, 0
	v_max_f32_e64 v2, |v2|, |v2|
	v_mul_f32_e32 v0, 0x41000000, v0
	v_mov_b32_dpp v5, v4 quad_perm:[1,0,3,2] row_mask:0xf bank_mask:0xf
	v_max_f32_e32 v4, v5, v5
	v_max_f32_e32 v2, v2, v4
	v_mov_b32_e32 v4, 0
	v_mov_b32_e32 v5, 0
	v_mul_f32_e32 v0, v0, v1
	v_mov_b32_dpp v4, v2 quad_perm:[2,3,0,1] row_mask:0xf bank_mask:0xf
	v_max_f32_e32 v4, v4, v4
	v_max_f32_e32 v2, v2, v4
	v_mov_b32_e32 v4, 0
	v_mul_f32_e32 v1, 0x41000000, v3
	v_readfirstlane_b32 s3, v0
	v_mov_b32_dpp v4, v2 row_half_mirror row_mask:0xf bank_mask:0xf
	v_max_f32_e32 v4, v4, v4
	v_max_f32_e32 v2, v2, v4
	v_mov_b32_e32 v4, 0
	s_nop 1
	v_mov_b32_dpp v4, v2 row_mirror row_mask:0xf bank_mask:0xf
	v_max_f32_e32 v4, v4, v4
	v_max_f32_e32 v2, v2, v4
	v_mov_b32_e32 v4, v2
	s_nop 1
	v_permlane16_swap_b32_e32 v2, v4
	v_max_f32_e32 v4, v4, v4
	v_max_f32_e32 v2, v2, v2
	v_max_f32_e32 v2, v2, v4
	v_mov_b32_e32 v4, v2
	s_nop 1
	v_permlane32_swap_b32_e32 v2, v4
	v_max_f32_e32 v4, v4, v4
	v_max_f32_e32 v2, v2, v2
	v_max_f32_e32 v2, v2, v4
	s_waitcnt vmcnt(2)
	v_mul_f32_e32 v4, v19, v20
	v_mul_f32_e32 v1, v1, v2
	s_nop 0
	v_mov_b32_dpp v5, v4 quad_perm:[1,0,3,2] row_mask:0xf bank_mask:0xf
	v_fmac_f32_e32 v5, v19, v20
	s_nop 1
	v_add_f32_dpp v4, v5, v5 quad_perm:[2,3,0,1] row_mask:0xf bank_mask:0xf bound_ctrl:1
	s_nop 1
	v_add_f32_dpp v4, v4, v4 row_half_mirror row_mask:0xf bank_mask:0xf bound_ctrl:1
	s_nop 1
	v_add_f32_dpp v4, v4, v4 row_mirror row_mask:0xf bank_mask:0xf bound_ctrl:1
	v_mov_b32_e32 v5, v4
	s_nop 1
	v_permlane16_swap_b32_e32 v4, v5
	v_add_f32_e32 v4, v4, v5
	v_mov_b32_e32 v5, v4
	s_nop 1
	v_permlane32_swap_b32_e32 v4, v5
	v_add_f32_e32 v4, v4, v5
	s_waitcnt vmcnt(0)
	v_mul_f32_e32 v5, v21, v22
	v_cmp_ngt_f32_e32 vcc, s0, v4
	s_nop 0
	v_mov_b32_dpp v7, v5 quad_perm:[1,0,3,2] row_mask:0xf bank_mask:0xf
	v_fmac_f32_e32 v7, v21, v22
	s_nop 1
	v_add_f32_dpp v5, v7, v7 quad_perm:[2,3,0,1] row_mask:0xf bank_mask:0xf bound_ctrl:1
	s_nop 1
	v_add_f32_dpp v5, v5, v5 row_half_mirror row_mask:0xf bank_mask:0xf bound_ctrl:1
	s_nop 1
	v_add_f32_dpp v5, v5, v5 row_mirror row_mask:0xf bank_mask:0xf bound_ctrl:1
	v_mov_b32_e32 v6, v5
	s_nop 1
	v_permlane16_swap_b32_e32 v5, v6
	v_add_f32_e32 v5, v5, v6
	v_mov_b32_e32 v6, v5
	s_nop 1
	v_permlane32_swap_b32_e32 v5, v6
	v_add_f32_e32 v5, v5, v6
	v_mul_f32_e32 v6, 0x3fb8aa3b, v4
	v_fma_f32 v7, v4, s2, -v6
	v_rndne_f32_e32 v8, v6
	v_fmac_f32_e32 v7, 0x32a5705f, v4
	v_sub_f32_e32 v6, v6, v8
	v_add_f32_e32 v6, v6, v7
	v_exp_f32_e32 v6, v6
	v_cvt_i32_f32_e32 v7, v8
	v_ldexp_f32 v6, v6, v7
	v_mul_f32_e32 v7, 0x3fb8aa3b, v5
	v_fma_f32 v8, v5, s2, -v7
	v_rndne_f32_e32 v9, v7
	v_fmac_f32_e32 v8, 0x32a5705f, v5
	v_sub_f32_e32 v7, v7, v9
	v_add_f32_e32 v7, v7, v8
	v_exp_f32_e32 v7, v7
	v_cvt_i32_f32_e32 v8, v9
	v_cndmask_b32_e32 v6, 0, v6, vcc
	v_mov_b32_e32 v9, 0x7f800000
	v_cmp_nlt_f32_e32 vcc, s1, v4
	v_readfirstlane_b32 s2, v1
	s_nop 0
	v_cndmask_b32_e32 v4, v9, v6, vcc
	v_ldexp_f32 v6, v7, v8
	v_cmp_ngt_f32_e32 vcc, s0, v5
	s_nop 1
	v_cndmask_b32_e32 v6, 0, v6, vcc
	v_cmp_nlt_f32_e32 vcc, s1, v5
	s_mov_b64 s[0:1], s[46:47]
	s_load_dwordx2 s[0:1], s[0:1], 0x98
	v_cndmask_b32_e32 v5, v9, v6, vcc
	v_sub_f32_e32 v4, v4, v5
	v_cmp_eq_u32_e32 vcc, 0, v150
	v_readfirstlane_b32 s12, v4
	s_waitcnt lgkmcnt(0)
	s_add_u32 s0, s0, 0x3840
	s_addc_u32 s1, s1, 0
	v_writelane_b32 v251, s0, 17
	s_barrier
	s_nop 0
	v_writelane_b32 v251, s1, 18
	s_and_saveexec_b64 s[0:1], vcc
	s_cbranch_execz .LBB0_349
	s_mov_b64 s[10:11], exec
	v_mbcnt_lo_u32_b32 v0, s10, 0
	v_mbcnt_hi_u32_b32 v0, s11, v0
	v_cmp_eq_u32_e32 vcc, 0, v0
	s_and_saveexec_b64 s[8:9], vcc
	s_cbranch_execz .LBB0_348
	s_bcnt1_i32_b64 s10, s[10:11]
	v_mov_b32_e32 v2, s10
	v_readlane_b32 s10, v251, 17
	v_mov_b32_e32 v1, 0
	v_readlane_b32 s11, v251, 18
	s_nop 4
	global_atomic_add v1, v1, v2, s[10:11] sc0

; template <int TYPE> __device__ __forceinline__ void attn_unit(const AttnCtx& C, int b, int h, int qb, LAS unsigned char* lds, int tid_in, unsigned* counter) {
;     ...
;             const bool active = (TYPE == 2) ? (t >= cq - 8 && t <= cq) : (TYPE == 0) ? (t <= cq && (float)(256 * qb + 32 * w - 64 * t - 63) < dmax) : (t <= cq && t >= tfirst);
;             if (active) {
;                 f32x16 p0, p1;
;                 const LAS unsigned char* kp = Kb + bo + hi * 1024 + r32 * 16;
; #pragma unroll
;                 for (int d0 = 0; d0 < 4; ++d0) {
;                     const bf16x8 a0 = *(const LAS bf16x8*)(kp + d0 * 2048), a1 = *(const LAS bf16x8*)(kp + d0 * 2048 + 512);
;                     if (d0 == 0) { p0 = MFMA32(a0, qr[0], (TYPE == 1 ? cvec : zvec)); p1 = MFMA32(a1, qr[0], (TYPE == 1 ? cvec : zvec)); }
;                     else { p0 = MFMA32(a0, qr[d0], p0); p1 = MFMA32(a1, qr[d0], p1); }
;                 }
;                 const int xi = sq - 64 * t - 4 * hi;
;                 if (TYPE == 0) {
;                     const float xf = (float)xi;
; #pragma unroll
;                     for (int r = 0; r < 16; ++r) { const float c = (float)((r & 3) + 8 * (r >> 2));
;                         p0[r] = fast_exp2(p0[r] - sl2 * fabsf(xf - c)); p1[r] = fast_exp2(p1[r] - sl2 * fabsf(xf - (c + 32.f))); }
;                 } else if (TYPE == 1) {
;                     const LAS float* fp = Fb + (t & 3) * 64 + 4 * hi;
; #pragma unroll
;                     for (int g = 0; g < 4; ++g) { const f32x4 fa = *(const LAS f32x4*)(fp + 8 * g), fb2 = *(const LAS f32x4*)(fp + 32 + 8 * g);
; #pragma unroll
;                         for (int i = 0; i < 4; i += 2) {
;                             const f32x2_t d0_ = (f32x2_t){p0[4 * g + i], p0[4 * g + i + 1]} - (f32x2_t){fa[i], fa[i + 1]}, d1_ = (f32x2_t){p1[4 * g + i], p1[4 * g + i + 1]} - (f32x2_t){fb2[i], fb2[i + 1]};
;                             p0[4 * g + i] = fast_exp2(d0_[0]); p0[4 * g + i + 1] = fast_exp2(d0_[1]); p1[4 * g + i] = fast_exp2(d1_[0]); p1[4 * g + i + 1] = fast_exp2(d1_[1]); } }
;                     if (t == cq) { const int qrel = 32 * (w & 1) + r32;
; #pragma unroll
;                         for (int r = 0; r < 16; ++r) { const int kv = crow(r, hi); if (kv > qrel) p0[r] = 0.f; if (kv + 32 > qrel) p1[r] = 0.f; } }
;                 } else {
;                     if (cq - t >= 3) { const float bc = relb[256];
.LBB0_438:
	s_cmp_gt_i32 s4, s14
	s_cbranch_scc1 .LBB0_433
	s_sub_i32 s6, s1, 63
	v_cvt_f32_i32_e32 v32, s6
	v_cmp_ngt_f32_e32 vcc, v168, v32
	s_cbranch_vccnz .LBB0_433
	s_cmp_eq_u32 s4, s14
	s_cbranch_scc1 .Lt0diag_4
	v_add_u32_e32 v118, s5, v171
	v_add_u32_e32 v213, s1, v172
	v_cvt_f32_i32_e32 v213, v213
	v_mul_f32_e64 v210, -v167, v213
	ds_read_b128 v[202:205], v118
	ds_read_b128 v[206:209], v118 offset:512
	ds_read_b128 v[110:113], v118 offset:2048
	ds_read_b128 v[114:117], v118 offset:2560
	v_add_u32_e32 v134, s5, v170
	v_mov_b32_e32 v48, v210
	v_fmamk_f32 v49, v167, 0x3f800000, v210
	v_fmamk_f32 v50, v167, 0x40000000, v210
	v_fmamk_f32 v51, v167, 0x40400000, v210
	v_fmamk_f32 v52, v167, 0x41000000, v210
	v_fmamk_f32 v53, v167, 0x41100000, v210
	v_fmamk_f32 v54, v167, 0x41200000, v210
	v_fmamk_f32 v55, v167, 0x41300000, v210
	v_fmamk_f32 v56, v167, 0x41800000, v210
	v_fmamk_f32 v57, v167, 0x41880000, v210
	v_fmamk_f32 v58, v167, 0x41900000, v210
	v_fmamk_f32 v59, v167, 0x41980000, v210
	v_fmamk_f32 v60, v167, 0x41c00000, v210
	v_fmamk_f32 v61, v167, 0x41c80000, v210
	v_fmamk_f32 v62, v167, 0x41d00000, v210
	v_fmamk_f32 v63, v167, 0x41d80000, v210
	v_fmamk_f32 v32, v167, 0x42000000, v210
	v_fmamk_f32 v33, v167, 0x42040000, v210
	v_fmamk_f32 v34, v167, 0x42080000, v210
	v_fmamk_f32 v35, v167, 0x420c0000, v210
	v_fmamk_f32 v36, v167, 0x42200000, v210
	v_fmamk_f32 v37, v167, 0x42240000, v210
	v_fmamk_f32 v38, v167, 0x42280000, v210
	v_fmamk_f32 v39, v167, 0x422c0000, v210
	v_fmamk_f32 v40, v167, 0x42400000, v210
	v_fmamk_f32 v41, v167, 0x42440000, v210
	v_fmamk_f32 v42, v167, 0x42480000, v210
	v_fmamk_f32 v43, v167, 0x424c0000, v210
	v_fmamk_f32 v44, v167, 0x42600000, v210
	v_fmamk_f32 v45, v167, 0x42640000, v210
	v_fmamk_f32 v46, v167, 0x42680000, v210
	v_fmamk_f32 v47, v167, 0x426c0000, v210
	s_waitcnt vmcnt(7) lgkmcnt(3)
	v_mfma_f32_32x32x16_bf16 v[48:63], v[202:205], v[64:67], v[48:63]
	s_waitcnt lgkmcnt(2)
	v_mfma_f32_32x32x16_bf16 v[32:47], v[206:209], v[64:67], v[32:47]
	s_waitcnt vmcnt(6) lgkmcnt(0)
	v_mfma_f32_32x32x16_bf16 v[32:47], v[114:117], v[68:71], v[32:47]
	v_mfma_f32_32x32x16_bf16 v[48:63], v[110:113], v[68:71], v[48:63]
	ds_read_b128 v[110:113], v118 offset:4096
	ds_read_b128 v[114:117], v118 offset:4608
	s_waitcnt vmcnt(5) lgkmcnt(0)
	v_mfma_f32_32x32x16_bf16 v[32:47], v[114:117], v[72:75], v[32:47]
	v_mfma_f32_32x32x16_bf16 v[48:63], v[110:113], v[72:75], v[48:63]
	ds_read_b128 v[110:113], v118 offset:6144
	ds_read_b128 v[114:117], v118 offset:6656
	s_waitcnt vmcnt(4) lgkmcnt(0)
	v_mfma_f32_32x32x16_bf16 v[32:47], v[114:117], v[76:79], v[32:47]
	v_mfma_f32_32x32x16_bf16 v[48:63], v[110:113], v[76:79], v[48:63]
	s_nop 11
	v_exp_f32_e32 v32, v32
	v_exp_f32_e32 v110, v52
	v_exp_f32_e32 v112, v36
	v_exp_f32_e32 v111, v53
	v_exp_f32_e32 v113, v37
	v_exp_f32_e32 v114, v54
	v_exp_f32_e32 v116, v38
	v_exp_f32_e32 v115, v55
	v_exp_f32_e32 v117, v39
	v_exp_f32_e32 v118, v56
	v_exp_f32_e32 v120, v40
	v_exp_f32_e32 v119, v57
	v_exp_f32_e32 v121, v41
	v_exp_f32_e32 v122, v58
	v_exp_f32_e32 v124, v42
	v_exp_f32_e32 v123, v59
	v_exp_f32_e32 v125, v43
	v_exp_f32_e32 v126, v60
	v_exp_f32_e32 v128, v44
	v_exp_f32_e32 v127, v61
	v_exp_f32_e32 v129, v45
	v_exp_f32_e32 v48, v48
	v_exp_f32_e32 v49, v49
	v_exp_f32_e32 v50, v50
	v_exp_f32_e32 v51, v51
	v_exp_f32_e32 v130, v62
	v_exp_f32_e32 v132, v46
	v_exp_f32_e32 v131, v63
	v_cvt_pk_bf16_f32 v36, v48, v49
	v_cvt_pk_bf16_f32 v37, v50, v51
	v_cvt_pk_bf16_f32 v38, v110, v111
	v_cvt_pk_bf16_f32 v39, v114, v115
	ds_read_b64_tr_b16 v[40:41], v134 offset:32768
	ds_read_b64_tr_b16 v[42:43], v134 offset:33280
	s_waitcnt lgkmcnt(0)
	v_mfma_f32_32x32x16_bf16 v[16:31], v[36:39], v[40:43], v[16:31]
	v_cvt_pk_bf16_f32 v52, v118, v119
	ds_read_b64_tr_b16 v[56:57], v134 offset:33792
	ds_read_b64_tr_b16 v[58:59], v134 offset:34304
	v_cvt_pk_bf16_f32 v53, v122, v123
	v_cvt_pk_bf16_f32 v54, v126, v127
	v_cvt_pk_bf16_f32 v55, v130, v131
	v_exp_f32_e32 v33, v33
	v_exp_f32_e32 v34, v34
	v_exp_f32_e32 v35, v35
	s_waitcnt lgkmcnt(0)
	v_mfma_f32_32x32x16_bf16 v[16:31], v[52:55], v[56:59], v[16:31]
	v_exp_f32_e32 v133, v47
	v_cvt_pk_bf16_f32 v40, v32, v33
	v_cvt_pk_bf16_f32 v41, v34, v35
	v_cvt_pk_bf16_f32 v42, v112, v113
	v_cvt_pk_bf16_f32 v43, v116, v117
	ds_read_b64_tr_b16 v[44:45], v134 offset:34816
	ds_read_b64_tr_b16 v[46:47], v134 offset:35328
	s_waitcnt lgkmcnt(0)
	v_mfma_f32_32x32x16_bf16 v[16:31], v[40:43], v[44:47], v[16:31]
	v_cvt_pk_bf16_f32 v56, v120, v121
	ds_read_b64_tr_b16 v[60:61], v134 offset:35840
	ds_read_b64_tr_b16 v[62:63], v134 offset:36352
	v_cvt_pk_bf16_f32 v57, v124, v125
	v_cvt_pk_bf16_f32 v58, v128, v129
	v_cvt_pk_bf16_f32 v59, v132, v133
	s_waitcnt lgkmcnt(0)
	s_nop 0
	v_mfma_f32_32x32x16_bf16 v[16:31], v[56:59], v[60:63], v[16:31]
	ds_read_b64_tr_b16 v[44:45], v134 offset:36864
	ds_read_b64_tr_b16 v[46:47], v134 offset:37376
	ds_read_b64_tr_b16 v[60:61], v134 offset:37888
	ds_read_b64_tr_b16 v[62:63], v134 offset:38400
	s_waitcnt lgkmcnt(2)
	v_mfma_f32_32x32x16_bf16 v[0:15], v[36:39], v[44:47], v[0:15]
	v_add_f32_e64 v36, v48, 0
	v_add_f32_e64 v37, v49, 0
	v_add_f32_e64 v32, v32, v36
	v_add_f32_e64 v33, v33, v37
	v_add_f32_e64 v32, v50, v32
	v_add_f32_e64 v33, v51, v33
	v_pk_add_f32 v[32:33], v[34:35], v[32:33]
	s_waitcnt lgkmcnt(0)
	v_mfma_f32_32x32x16_bf16 v[0:15], v[52:55], v[60:63], v[0:15]
	v_add_f32_e64 v32, v110, v32
	v_add_f32_e64 v33, v111, v33
	v_add_f32_e64 v32, v112, v32
	v_add_f32_e64 v33, v113, v33
	v_add_f32_e64 v32, v114, v32
	v_add_f32_e64 v33, v115, v33
	v_pk_add_f32 v[36:37], v[116:117], v[32:33]
	ds_read_b64_tr_b16 v[32:33], v134 offset:38912
	ds_read_b64_tr_b16 v[34:35], v134 offset:39424
	s_waitcnt lgkmcnt(0)
	v_mfma_f32_32x32x16_bf16 v[0:15], v[40:43], v[32:35], v[0:15]
	v_add_f32_e64 v36, v118, v36
	v_add_f32_e64 v37, v119, v37
	v_add_f32_e64 v44, v120, v36
	v_add_f32_e64 v45, v121, v37
	ds_read_b64_tr_b16 v[36:37], v134 offset:39936
	ds_read_b64_tr_b16 v[38:39], v134 offset:40448
	v_pk_add_f32 v[32:33], v[122:123], v[44:45]
	s_nop 0
	v_pk_add_f32 v[32:33], v[124:125], v[32:33]
	s_waitcnt lgkmcnt(0)
	v_mfma_f32_32x32x16_bf16 v[0:15], v[56:59], v[36:39], v[0:15]
	v_add_f32_e64 v32, v126, v32
	v_add_f32_e64 v33, v127, v33
	v_add_f32_e64 v32, v128, v32
	v_add_f32_e64 v33, v129, v33
	v_add_f32_e64 v32, v130, v32
	v_add_f32_e64 v33, v131, v33
	v_pk_add_f32 v[32:33], v[132:133], v[32:33]
	s_nop 0
	v_add_f32_e32 v32, v32, v33
	v_add_f32_e32 v109, v109, v32
	s_branch .LBB0_433
; #define LAS __attribute__((address_space(3)))
; __device__ __forceinline__ float fast_exp2(float x) { return __builtin_amdgcn_exp2f(x); }
; #define MFMA32(a, b, c) __builtin_amdgcn_mfma_f32_32x32x16_bf16((a), (b), (c), 0, 0, 0)
; template <int TYPE> __device__ __forceinline__ void attn_unit(const AttnCtx& C, int b, int h, int qb, LAS unsigned char* lds, int tid_in, unsigned* counter) {
;     ...
;                 f32x16 p0, p1;
;                 const LAS unsigned char* kp = Kb + bo + hi * 1024 + r32 * 16;
; #pragma unroll
;                 for (int d0 = 0; d0 < 4; ++d0) {
;                     const bf16x8 a0 = *(const LAS bf16x8*)(kp + d0 * 2048), a1 = *(const LAS bf16x8*)(kp + d0 * 2048 + 512);
;                     if (d0 == 0) { p0 = MFMA32(a0, qr[0], (TYPE == 1 ? cvec : zvec)); p1 = MFMA32(a1, qr[0], (TYPE == 1 ? cvec : zvec)); }
;                     else { p0 = MFMA32(a0, qr[d0], p0); p1 = MFMA32(a1, qr[d0], p1); }
;                 }
;                 const int xi = sq - 64 * t - 4 * hi;
;                 if (TYPE == 0) {
;                     const float xf = (float)xi;
; #pragma unroll
;                     for (int r = 0; r < 16; ++r) { const float c = (float)((r & 3) + 8 * (r >> 2));
;                         p0[r] = fast_exp2(p0[r] - sl2 * fabsf(xf - c)); p1[r] = fast_exp2(p1[r] - sl2 * fabsf(xf - (c + 32.f))); }
.Lt0diag_4:
	v_add_u32_e32 v118, s5, v171
	ds_read_b128 v[32:35], v118
	ds_read_b128 v[36:39], v118 offset:512
	ds_read_b128 v[110:113], v118 offset:2048
	ds_read_b128 v[114:117], v118 offset:2560
	v_add_u32_e32 v134, s5, v170
	s_waitcnt vmcnt(7) lgkmcnt(3)
	v_mfma_f32_32x32x16_bf16 v[48:63], v[32:35], v[64:67], 0
	s_waitcnt lgkmcnt(2)
	v_mfma_f32_32x32x16_bf16 v[32:47], v[36:39], v[64:67], 0
	s_waitcnt vmcnt(6) lgkmcnt(0)
	v_mfma_f32_32x32x16_bf16 v[32:47], v[114:117], v[68:71], v[32:47]
	v_mfma_f32_32x32x16_bf16 v[48:63], v[110:113], v[68:71], v[48:63]
	ds_read_b128 v[110:113], v118 offset:4096
	ds_read_b128 v[114:117], v118 offset:4608
	s_waitcnt vmcnt(5) lgkmcnt(0)
	v_mfma_f32_32x32x16_bf16 v[32:47], v[114:117], v[72:75], v[32:47]
	v_mfma_f32_32x32x16_bf16 v[48:63], v[110:113], v[72:75], v[48:63]
	ds_read_b128 v[110:113], v118 offset:6144
	ds_read_b128 v[114:117], v118 offset:6656
	v_add_u32_e32 v118, s1, v172
	v_cvt_f32_i32_e32 v133, v118
	s_waitcnt vmcnt(4) lgkmcnt(0)
	v_mfma_f32_32x32x16_bf16 v[32:47], v[114:117], v[76:79], v[32:47]
	v_mfma_f32_32x32x16_bf16 v[48:63], v[110:113], v[76:79], v[48:63]
	v_add_f32_e32 v110, 0xc2000000, v133
	s_nop 9
	v_fma_f32 v32, -v167, |v110|, v32
	v_add_f32_e32 v110, -1.0, v133
	v_exp_f32_e32 v32, v32
	v_fma_f32 v49, -v167, |v110|, v49
	v_add_f32_e32 v110, 0xc2040000, v133
	v_fma_f32 v33, -v167, |v110|, v33
	v_add_f32_e32 v110, -2.0, v133
	v_fma_f32 v50, -v167, |v110|, v50
	v_add_f32_e32 v110, 0xc2080000, v133
	v_fma_f32 v34, -v167, |v110|, v34
	v_add_f32_e32 v110, 0xc0400000, v133
	v_fma_f32 v51, -v167, |v110|, v51
	v_add_f32_e32 v110, 0xc20c0000, v133
	v_fma_f32 v35, -v167, |v110|, v35
	v_add_f32_e32 v110, 0xc1000000, v133
	v_fma_f32 v52, -v167, |v110|, v52
	v_exp_f32_e32 v110, v52
	v_add_f32_e32 v52, 0xc2200000, v133
	v_fma_f32 v36, -v167, |v52|, v36
	v_exp_f32_e32 v112, v36
	v_add_f32_e32 v36, 0xc1100000, v133
	v_fma_f32 v36, -v167, |v36|, v53
	v_exp_f32_e32 v111, v36
	v_add_f32_e32 v36, 0xc2240000, v133
	v_fma_f32 v36, -v167, |v36|, v37
	v_exp_f32_e32 v113, v36
	v_add_f32_e32 v36, 0xc1200000, v133
	v_fma_f32 v36, -v167, |v36|, v54
	v_exp_f32_e32 v114, v36
	v_add_f32_e32 v36, 0xc2280000, v133
	v_fma_f32 v36, -v167, |v36|, v38
	v_exp_f32_e32 v116, v36
	v_add_f32_e32 v36, 0xc1300000, v133
	v_fma_f32 v36, -v167, |v36|, v55
	v_exp_f32_e32 v115, v36
	v_add_f32_e32 v36, 0xc22c0000, v133
	v_fma_f32 v36, -v167, |v36|, v39
	v_exp_f32_e32 v117, v36
	v_add_f32_e32 v36, 0xc1800000, v133
	v_fma_f32 v36, -v167, |v36|, v56
	v_exp_f32_e32 v118, v36
	v_add_f32_e32 v36, 0xc2400000, v133
	v_fma_f32 v36, -v167, |v36|, v40
	v_exp_f32_e32 v120, v36
	v_add_f32_e32 v36, 0xc1880000, v133
	v_fma_f32 v36, -v167, |v36|, v57
	v_exp_f32_e32 v119, v36
	v_add_f32_e32 v36, 0xc2440000, v133
	v_fma_f32 v36, -v167, |v36|, v41
	v_exp_f32_e32 v121, v36
	v_add_f32_e32 v36, 0xc1900000, v133
	v_fma_f32 v36, -v167, |v36|, v58
	v_exp_f32_e32 v122, v36
	v_add_f32_e32 v36, 0xc2480000, v133
	v_fma_f32 v36, -v167, |v36|, v42
	v_exp_f32_e32 v124, v36
	v_add_f32_e32 v36, 0xc1980000, v133
	v_fma_f32 v36, -v167, |v36|, v59
	v_exp_f32_e32 v123, v36
	v_add_f32_e32 v36, 0xc24c0000, v133
	v_fma_f32 v36, -v167, |v36|, v43
	v_exp_f32_e32 v125, v36
	v_add_f32_e32 v36, 0xc1c00000, v133
	v_fma_f32 v36, -v167, |v36|, v60
	v_exp_f32_e32 v126, v36
	v_add_f32_e32 v36, 0xc2600000, v133
	v_fma_f32 v36, -v167, |v36|, v44
	v_exp_f32_e32 v128, v36
	v_add_f32_e32 v36, 0xc1c80000, v133
	v_fma_f32 v36, -v167, |v36|, v61
	v_exp_f32_e32 v127, v36
	v_add_f32_e32 v36, 0xc2640000, v133
	v_fma_f32 v36, -v167, |v36|, v45
	v_exp_f32_e32 v129, v36
	v_add_f32_e32 v36, 0xc1d00000, v133
	v_fma_f32 v48, -v167, |v133|, v48
	v_fma_f32 v36, -v167, |v36|, v62
	v_exp_f32_e32 v48, v48
	v_exp_f32_e32 v49, v49
	v_exp_f32_e32 v50, v50
	v_exp_f32_e32 v51, v51
	v_exp_f32_e32 v130, v36
	v_add_f32_e32 v36, 0xc2680000, v133
	v_fma_f32 v36, -v167, |v36|, v46
	v_exp_f32_e32 v132, v36
	v_add_f32_e32 v36, 0xc1d80000, v133
	v_fma_f32 v36, -v167, |v36|, v63
	v_exp_f32_e32 v131, v36
	v_cvt_pk_bf16_f32 v36, v48, v49
	v_cvt_pk_bf16_f32 v37, v50, v51
	v_cvt_pk_bf16_f32 v38, v110, v111
	v_cvt_pk_bf16_f32 v39, v114, v115
	ds_read_b64_tr_b16 v[40:41], v134 offset:32768
	ds_read_b64_tr_b16 v[42:43], v134 offset:33280
	s_waitcnt lgkmcnt(0)
; #define LAS __attribute__((address_space(3)))
; __device__ __forceinline__ unsigned pk2(float lo, float hi) { f32x2_t v = {lo, hi}; bf16x2_t b = __builtin_convertvector(v, bf16x2_t); return __builtin_bit_cast(unsigned, b); }
; #define MFMA32(a, b, c) __builtin_amdgcn_mfma_f32_32x32x16_bf16((a), (b), (c), 0, 0, 0)
; __device__ __forceinline__ s16x4 vtr(const LAS unsigned char* p) { return __builtin_bit_cast(s16x4, __builtin_amdgcn_ds_read_tr16_b64_v4i16((LAS v4i16_t*)p)); }
; template <int TYPE> __device__ __forceinline__ void attn_unit(const AttnCtx& C, int b, int h, int qb, LAS unsigned char* lds, int tid_in, unsigned* counter) {
;     ...
;                 f32x2_t a2 = {0.f, 0.f};
; #pragma unroll
;                 for (int r = 0; r < 16; r += 2) { a2 += (f32x2_t){p0[r], p0[r + 1]}; a2 += (f32x2_t){p1[r], p1[r + 1]}; }
;                 lsum += a2[0] + a2[1];
;                 bf16x8 pa[4];
; #pragma unroll
;                 for (int s = 0; s < 2; ++s) {
;                     u32x4 a, c2;
;                     a.x = pk2(p0[8 * s + 0], p0[8 * s + 1]); a.y = pk2(p0[8 * s + 2], p0[8 * s + 3]); a.z = pk2(p0[8 * s + 4], p0[8 * s + 5]); a.w = pk2(p0[8 * s + 6], p0[8 * s + 7]);
;                     c2.x = pk2(p1[8 * s + 0], p1[8 * s + 1]); c2.y = pk2(p1[8 * s + 2], p1[8 * s + 3]); c2.z = pk2(p1[8 * s + 4], p1[8 * s + 5]); c2.w = pk2(p1[8 * s + 6], p1[8 * s + 7]);
;                     pa[s] = __builtin_bit_cast(bf16x8, a); pa[2 + s] = __builtin_bit_cast(bf16x8, c2);
;                 }
;                 const LAS unsigned char* vp = Vb + bo + vb0;
; #pragma unroll
;                 for (int dh = 0; dh < 2; ++dh)
; #pragma unroll
;                     for (int ks = 0; ks < 4; ++ks) {
;                         const s16x4 lo = vtr(vp + dh * 4096 + ks * 1024), hh = vtr(vp + dh * 4096 + ks * 1024 + 512);
;                         const bf16x8 vf = {lo[0], lo[1], lo[2], lo[3], hh[0], hh[1], hh[2], hh[3]};
;                         o[dh] = MFMA32(pa[ks], vf, o[dh]);
;                     }
	v_mfma_f32_32x32x16_bf16 v[16:31], v[36:39], v[40:43], v[16:31]
	v_cvt_pk_bf16_f32 v52, v118, v119
	ds_read_b64_tr_b16 v[56:57], v134 offset:33792
	ds_read_b64_tr_b16 v[58:59], v134 offset:34304
	v_cvt_pk_bf16_f32 v53, v122, v123
	v_cvt_pk_bf16_f32 v54, v126, v127
	v_cvt_pk_bf16_f32 v55, v130, v131
	v_exp_f32_e32 v33, v33
	v_exp_f32_e32 v34, v34
	v_exp_f32_e32 v35, v35
	s_waitcnt lgkmcnt(0)
	v_mfma_f32_32x32x16_bf16 v[16:31], v[52:55], v[56:59], v[16:31]
	v_add_f32_e32 v44, 0xc26c0000, v133
	v_fma_f32 v60, -v167, |v44|, v47
	v_cvt_pk_bf16_f32 v40, v32, v33
	v_cvt_pk_bf16_f32 v41, v34, v35
	v_cvt_pk_bf16_f32 v42, v112, v113
	v_cvt_pk_bf16_f32 v43, v116, v117
	ds_read_b64_tr_b16 v[44:45], v134 offset:34816
	ds_read_b64_tr_b16 v[46:47], v134 offset:35328
	v_exp_f32_e32 v133, v60
	s_waitcnt lgkmcnt(0)
	v_mfma_f32_32x32x16_bf16 v[16:31], v[40:43], v[44:47], v[16:31]
	v_cvt_pk_bf16_f32 v56, v120, v121
	ds_read_b64_tr_b16 v[60:61], v134 offset:35840
	ds_read_b64_tr_b16 v[62:63], v134 offset:36352
	v_cvt_pk_bf16_f32 v57, v124, v125
	v_cvt_pk_bf16_f32 v58, v128, v129
	v_cvt_pk_bf16_f32 v59, v132, v133
	s_waitcnt lgkmcnt(0)
	s_nop 0
	v_mfma_f32_32x32x16_bf16 v[16:31], v[56:59], v[60:63], v[16:31]
	ds_read_b64_tr_b16 v[44:45], v134 offset:36864
	ds_read_b64_tr_b16 v[46:47], v134 offset:37376
	ds_read_b64_tr_b16 v[60:61], v134 offset:37888
	ds_read_b64_tr_b16 v[62:63], v134 offset:38400
	s_waitcnt lgkmcnt(2)
	v_mfma_f32_32x32x16_bf16 v[0:15], v[36:39], v[44:47], v[0:15]
	v_add_f32_e64 v36, v48, 0
	v_add_f32_e64 v37, v49, 0
	v_add_f32_e64 v32, v32, v36
	v_add_f32_e64 v33, v33, v37
	v_add_f32_e64 v32, v50, v32
	v_add_f32_e64 v33, v51, v33
	v_pk_add_f32 v[32:33], v[34:35], v[32:33]
	s_waitcnt lgkmcnt(0)
	v_mfma_f32_32x32x16_bf16 v[0:15], v[52:55], v[60:63], v[0:15]
	v_add_f32_e64 v32, v110, v32
	v_add_f32_e64 v33, v111, v33
	v_add_f32_e64 v32, v112, v32
	v_add_f32_e64 v33, v113, v33
	v_add_f32_e64 v32, v114, v32
	v_add_f32_e64 v33, v115, v33
	v_pk_add_f32 v[36:37], v[116:117], v[32:33]
	ds_read_b64_tr_b16 v[32:33], v134 offset:38912
	ds_read_b64_tr_b16 v[34:35], v134 offset:39424
	s_waitcnt lgkmcnt(0)
	v_mfma_f32_32x32x16_bf16 v[0:15], v[40:43], v[32:35], v[0:15]
	v_add_f32_e64 v36, v118, v36
	v_add_f32_e64 v37, v119, v37
	v_add_f32_e64 v44, v120, v36
	v_add_f32_e64 v45, v121, v37
	ds_read_b64_tr_b16 v[36:37], v134 offset:39936
	ds_read_b64_tr_b16 v[38:39], v134 offset:40448
	v_pk_add_f32 v[32:33], v[122:123], v[44:45]
	s_nop 0
	v_pk_add_f32 v[32:33], v[124:125], v[32:33]
	s_waitcnt lgkmcnt(0)
	v_mfma_f32_32x32x16_bf16 v[0:15], v[56:59], v[36:39], v[0:15]
	v_add_f32_e64 v32, v126, v32
	v_add_f32_e64 v33, v127, v33
	v_add_f32_e64 v32, v128, v32
	v_add_f32_e64 v33, v129, v33
	v_add_f32_e64 v32, v130, v32
	v_add_f32_e64 v33, v131, v33
	v_pk_add_f32 v[32:33], v[132:133], v[32:33]
	s_nop 0
	v_add_f32_e32 v32, v32, v33
	v_add_f32_e32 v109, v109, v32
	s_branch .LBB0_433

; template <int TYPE> __device__ __forceinline__ void attn_unit(const AttnCtx& C, int b, int h, int qb, LAS unsigned char* lds, int tid_in, unsigned* counter) {
;     ...
;             const bool active = (TYPE == 2) ? (t >= cq - 8 && t <= cq) : (TYPE == 0) ? (t <= cq && (float)(256 * qb + 32 * w - 64 * t - 63) < dmax) : (t <= cq && t >= tfirst);
;             if (active) {
;                 f32x16 p0, p1;
;                 const LAS unsigned char* kp = Kb + bo + hi * 1024 + r32 * 16;
; #pragma unroll
;                 for (int d0 = 0; d0 < 4; ++d0) {
;                     const bf16x8 a0 = *(const LAS bf16x8*)(kp + d0 * 2048), a1 = *(const LAS bf16x8*)(kp + d0 * 2048 + 512);
;                     if (d0 == 0) { p0 = MFMA32(a0, qr[0], (TYPE == 1 ? cvec : zvec)); p1 = MFMA32(a1, qr[0], (TYPE == 1 ? cvec : zvec)); }
;                     else { p0 = MFMA32(a0, qr[d0], p0); p1 = MFMA32(a1, qr[d0], p1); }
;                 }
;                 const int xi = sq - 64 * t - 4 * hi;
;                 if (TYPE == 0) {
;                     const float xf = (float)xi;
; #pragma unroll
;                     for (int r = 0; r < 16; ++r) { const float c = (float)((r & 3) + 8 * (r >> 2));
;                         p0[r] = fast_exp2(p0[r] - sl2 * fabsf(xf - c)); p1[r] = fast_exp2(p1[r] - sl2 * fabsf(xf - (c + 32.f))); }
;                 } else if (TYPE == 1) {
;                     const LAS float* fp = Fb + (t & 3) * 64 + 4 * hi;
; #pragma unroll
;                     for (int g = 0; g < 4; ++g) { const f32x4 fa = *(const LAS f32x4*)(fp + 8 * g), fb2 = *(const LAS f32x4*)(fp + 32 + 8 * g);
; #pragma unroll
;                         for (int i = 0; i < 4; i += 2) {
;                             const f32x2_t d0_ = (f32x2_t){p0[4 * g + i], p0[4 * g + i + 1]} - (f32x2_t){fa[i], fa[i + 1]}, d1_ = (f32x2_t){p1[4 * g + i], p1[4 * g + i + 1]} - (f32x2_t){fb2[i], fb2[i + 1]};
;                             p0[4 * g + i] = fast_exp2(d0_[0]); p0[4 * g + i + 1] = fast_exp2(d0_[1]); p1[4 * g + i] = fast_exp2(d1_[0]); p1[4 * g + i + 1] = fast_exp2(d1_[1]); } }
;                     if (t == cq) { const int qrel = 32 * (w & 1) + r32;
; #pragma unroll
;                         for (int r = 0; r < 16; ++r) { const int kv = crow(r, hi); if (kv > qrel) p0[r] = 0.f; if (kv + 32 > qrel) p1[r] = 0.f; } }
;                 } else {
;                     if (cq - t >= 3) { const float bc = relb[256];
.LBB0_454:
	s_cmp_gt_i32 s15, s14
	s_cbranch_scc1 .LBB0_445
	s_sub_i32 s0, s6, 63
	s_waitcnt vmcnt(15)
	v_cvt_f32_i32_e32 v64, s0
	v_cmp_ngt_f32_e32 vcc, v168, v64
	s_cbranch_vccnz .LBB0_445
	s_cmp_eq_u32 s15, s14
	s_cbranch_scc1 .Lt0diag_3
	v_add_u32_e32 v184, s16, v171
	v_add_u32_e32 v213, s6, v172
	v_cvt_f32_i32_e32 v213, v213
	v_mul_f32_e64 v210, -v167, v213
	ds_read_b128 v[202:205], v184
	s_waitcnt vmcnt(14)
	ds_read_b128 v[206:209], v184 offset:512
	ds_read_b128 v[176:179], v184 offset:2048
	ds_read_b128 v[180:183], v184 offset:2560
	v_add_u32_e32 v200, s16, v170
	v_mov_b32_e32 v80, v210
	v_fmamk_f32 v81, v167, 0x3f800000, v210
	v_fmamk_f32 v82, v167, 0x40000000, v210
	v_fmamk_f32 v83, v167, 0x40400000, v210
	v_fmamk_f32 v84, v167, 0x41000000, v210
	v_fmamk_f32 v85, v167, 0x41100000, v210
	v_fmamk_f32 v86, v167, 0x41200000, v210
	v_fmamk_f32 v87, v167, 0x41300000, v210
	v_fmamk_f32 v88, v167, 0x41800000, v210
	v_fmamk_f32 v89, v167, 0x41880000, v210
	v_fmamk_f32 v90, v167, 0x41900000, v210
	v_fmamk_f32 v91, v167, 0x41980000, v210
	v_fmamk_f32 v92, v167, 0x41c00000, v210
	v_fmamk_f32 v93, v167, 0x41c80000, v210
	v_fmamk_f32 v94, v167, 0x41d00000, v210
	v_fmamk_f32 v95, v167, 0x41d80000, v210
	v_fmamk_f32 v64, v167, 0x42000000, v210
	v_fmamk_f32 v65, v167, 0x42040000, v210
	v_fmamk_f32 v66, v167, 0x42080000, v210
	v_fmamk_f32 v67, v167, 0x420c0000, v210
	v_fmamk_f32 v68, v167, 0x42200000, v210
	v_fmamk_f32 v69, v167, 0x42240000, v210
	v_fmamk_f32 v70, v167, 0x42280000, v210
	v_fmamk_f32 v71, v167, 0x422c0000, v210
	v_fmamk_f32 v72, v167, 0x42400000, v210
	v_fmamk_f32 v73, v167, 0x42440000, v210
	v_fmamk_f32 v74, v167, 0x42480000, v210
	v_fmamk_f32 v75, v167, 0x424c0000, v210
	v_fmamk_f32 v76, v167, 0x42600000, v210
	v_fmamk_f32 v77, v167, 0x42640000, v210
	v_fmamk_f32 v78, v167, 0x42680000, v210
	v_fmamk_f32 v79, v167, 0x426c0000, v210
	s_waitcnt vmcnt(7) lgkmcnt(3)
	v_mfma_f32_32x32x16_bf16 v[80:95], v[202:205], v[112:115], v[80:95]
	s_waitcnt lgkmcnt(2)
	v_mfma_f32_32x32x16_bf16 v[64:79], v[206:209], v[112:115], v[64:79]
	s_waitcnt vmcnt(6) lgkmcnt(0)
	v_mfma_f32_32x32x16_bf16 v[64:79], v[180:183], v[116:119], v[64:79]
	v_mfma_f32_32x32x16_bf16 v[80:95], v[176:179], v[116:119], v[80:95]
	ds_read_b128 v[176:179], v184 offset:4096
	ds_read_b128 v[180:183], v184 offset:4608
	s_waitcnt vmcnt(5) lgkmcnt(0)
	v_mfma_f32_32x32x16_bf16 v[64:79], v[180:183], v[120:123], v[64:79]
	v_mfma_f32_32x32x16_bf16 v[80:95], v[176:179], v[120:123], v[80:95]
	ds_read_b128 v[176:179], v184 offset:6144
	ds_read_b128 v[180:183], v184 offset:6656
	s_waitcnt vmcnt(4) lgkmcnt(0)
	v_mfma_f32_32x32x16_bf16 v[64:79], v[180:183], v[124:127], v[64:79]
	v_mfma_f32_32x32x16_bf16 v[80:95], v[176:179], v[124:127], v[80:95]
	s_nop 11
	v_exp_f32_e32 v64, v64
	v_exp_f32_e32 v176, v84
	v_exp_f32_e32 v178, v68
	v_exp_f32_e32 v177, v85
	v_exp_f32_e32 v179, v69
	v_exp_f32_e32 v180, v86
	v_exp_f32_e32 v182, v70
	v_exp_f32_e32 v181, v87
	v_exp_f32_e32 v183, v71
	v_exp_f32_e32 v184, v88
	v_exp_f32_e32 v186, v72
	v_exp_f32_e32 v185, v89
	v_exp_f32_e32 v187, v73
	v_exp_f32_e32 v188, v90
	v_exp_f32_e32 v190, v74
	v_exp_f32_e32 v189, v91
	v_exp_f32_e32 v191, v75
	v_exp_f32_e32 v192, v92
	v_exp_f32_e32 v194, v76
	v_exp_f32_e32 v193, v93
	v_exp_f32_e32 v195, v77
	v_exp_f32_e32 v80, v80
	v_exp_f32_e32 v81, v81
	v_exp_f32_e32 v82, v82
	v_exp_f32_e32 v83, v83
	v_exp_f32_e32 v196, v94
	v_exp_f32_e32 v198, v78
	v_exp_f32_e32 v197, v95
	v_cvt_pk_bf16_f32 v68, v80, v81
	v_cvt_pk_bf16_f32 v69, v82, v83
	v_cvt_pk_bf16_f32 v70, v176, v177
	v_cvt_pk_bf16_f32 v71, v180, v181
	ds_read_b64_tr_b16 v[72:73], v200 offset:32768
	ds_read_b64_tr_b16 v[74:75], v200 offset:33280
	s_waitcnt lgkmcnt(0)
	v_mfma_f32_32x32x16_bf16 v[48:63], v[68:71], v[72:75], v[48:63]
	v_cvt_pk_bf16_f32 v84, v184, v185
	ds_read_b64_tr_b16 v[88:89], v200 offset:33792
	ds_read_b64_tr_b16 v[90:91], v200 offset:34304
	v_cvt_pk_bf16_f32 v85, v188, v189
	v_cvt_pk_bf16_f32 v86, v192, v193
	v_cvt_pk_bf16_f32 v87, v196, v197
	v_exp_f32_e32 v65, v65
	v_exp_f32_e32 v66, v66
	v_exp_f32_e32 v67, v67
	s_waitcnt lgkmcnt(0)
	v_mfma_f32_32x32x16_bf16 v[48:63], v[84:87], v[88:91], v[48:63]
	v_exp_f32_e32 v199, v79
	v_cvt_pk_bf16_f32 v72, v64, v65
	v_cvt_pk_bf16_f32 v73, v66, v67
	v_cvt_pk_bf16_f32 v74, v178, v179
	v_cvt_pk_bf16_f32 v75, v182, v183
	ds_read_b64_tr_b16 v[76:77], v200 offset:34816
	ds_read_b64_tr_b16 v[78:79], v200 offset:35328
	s_waitcnt lgkmcnt(0)
	v_mfma_f32_32x32x16_bf16 v[48:63], v[72:75], v[76:79], v[48:63]
	v_cvt_pk_bf16_f32 v88, v186, v187
	ds_read_b64_tr_b16 v[92:93], v200 offset:35840
	ds_read_b64_tr_b16 v[94:95], v200 offset:36352
	v_cvt_pk_bf16_f32 v89, v190, v191
	v_cvt_pk_bf16_f32 v90, v194, v195
	v_cvt_pk_bf16_f32 v91, v198, v199
	s_waitcnt lgkmcnt(0)
	s_nop 0
	v_mfma_f32_32x32x16_bf16 v[48:63], v[88:91], v[92:95], v[48:63]
	ds_read_b64_tr_b16 v[76:77], v200 offset:36864
	ds_read_b64_tr_b16 v[78:79], v200 offset:37376
	ds_read_b64_tr_b16 v[92:93], v200 offset:37888
	ds_read_b64_tr_b16 v[94:95], v200 offset:38400
	s_waitcnt lgkmcnt(2)
	v_mfma_f32_32x32x16_bf16 v[32:47], v[68:71], v[76:79], v[32:47]
	v_add_f32_e64 v68, v80, 0
	v_add_f32_e64 v69, v81, 0
	v_add_f32_e64 v64, v64, v68
	v_add_f32_e64 v65, v65, v69
	v_add_f32_e64 v64, v82, v64
	v_add_f32_e64 v65, v83, v65
	v_pk_add_f32 v[64:65], v[66:67], v[64:65]
	s_waitcnt lgkmcnt(0)
	v_mfma_f32_32x32x16_bf16 v[32:47], v[84:87], v[92:95], v[32:47]
	v_add_f32_e64 v64, v176, v64
	v_add_f32_e64 v65, v177, v65
	v_add_f32_e64 v64, v178, v64
	v_add_f32_e64 v65, v179, v65
	v_add_f32_e64 v64, v180, v64
	v_add_f32_e64 v65, v181, v65
	v_pk_add_f32 v[68:69], v[182:183], v[64:65]
	ds_read_b64_tr_b16 v[64:65], v200 offset:38912
	ds_read_b64_tr_b16 v[66:67], v200 offset:39424
	s_waitcnt lgkmcnt(0)
	v_mfma_f32_32x32x16_bf16 v[32:47], v[72:75], v[64:67], v[32:47]
	v_add_f32_e64 v68, v184, v68
	v_add_f32_e64 v69, v185, v69
	v_add_f32_e64 v76, v186, v68
	v_add_f32_e64 v77, v187, v69
	ds_read_b64_tr_b16 v[68:69], v200 offset:39936
	ds_read_b64_tr_b16 v[70:71], v200 offset:40448
	v_pk_add_f32 v[64:65], v[188:189], v[76:77]
	s_nop 0
	v_pk_add_f32 v[64:65], v[190:191], v[64:65]
	s_waitcnt lgkmcnt(0)
	v_mfma_f32_32x32x16_bf16 v[32:47], v[88:91], v[68:71], v[32:47]
	v_add_f32_e64 v64, v192, v64
	v_add_f32_e64 v65, v193, v65
	v_add_f32_e64 v64, v194, v64
	v_add_f32_e64 v65, v195, v65
	v_add_f32_e64 v64, v196, v64
	v_add_f32_e64 v65, v197, v65
	v_pk_add_f32 v[64:65], v[198:199], v[64:65]
	s_nop 0
	v_add_f32_e32 v64, v64, v65
	v_add_f32_e32 v175, v175, v64
	s_branch .LBB0_445
; #define LAS __attribute__((address_space(3)))
; __device__ __forceinline__ float fast_exp2(float x) { return __builtin_amdgcn_exp2f(x); }
; #define MFMA32(a, b, c) __builtin_amdgcn_mfma_f32_32x32x16_bf16((a), (b), (c), 0, 0, 0)
; template <int TYPE> __device__ __forceinline__ void attn_unit(const AttnCtx& C, int b, int h, int qb, LAS unsigned char* lds, int tid_in, unsigned* counter) {
;     ...
;                 f32x16 p0, p1;
;                 const LAS unsigned char* kp = Kb + bo + hi * 1024 + r32 * 16;
; #pragma unroll
;                 for (int d0 = 0; d0 < 4; ++d0) {
;                     const bf16x8 a0 = *(const LAS bf16x8*)(kp + d0 * 2048), a1 = *(const LAS bf16x8*)(kp + d0 * 2048 + 512);
;                     if (d0 == 0) { p0 = MFMA32(a0, qr[0], (TYPE == 1 ? cvec : zvec)); p1 = MFMA32(a1, qr[0], (TYPE == 1 ? cvec : zvec)); }
;                     else { p0 = MFMA32(a0, qr[d0], p0); p1 = MFMA32(a1, qr[d0], p1); }
;                 }
;                 const int xi = sq - 64 * t - 4 * hi;
;                 if (TYPE == 0) {
;                     const float xf = (float)xi;
; #pragma unroll
;                     for (int r = 0; r < 16; ++r) { const float c = (float)((r & 3) + 8 * (r >> 2));
;                         p0[r] = fast_exp2(p0[r] - sl2 * fabsf(xf - c)); p1[r] = fast_exp2(p1[r] - sl2 * fabsf(xf - (c + 32.f))); }
.Lt0diag_3:
	v_add_u32_e32 v184, s16, v171
	ds_read_b128 v[64:67], v184
	s_waitcnt vmcnt(14)
	ds_read_b128 v[68:71], v184 offset:512
	ds_read_b128 v[176:179], v184 offset:2048
	ds_read_b128 v[180:183], v184 offset:2560
	v_add_u32_e32 v200, s16, v170
	s_waitcnt vmcnt(7) lgkmcnt(3)
	v_mfma_f32_32x32x16_bf16 v[80:95], v[64:67], v[112:115], 0
	s_waitcnt lgkmcnt(2)
	v_mfma_f32_32x32x16_bf16 v[64:79], v[68:71], v[112:115], 0
	s_waitcnt vmcnt(6) lgkmcnt(0)
	v_mfma_f32_32x32x16_bf16 v[64:79], v[180:183], v[116:119], v[64:79]
	v_mfma_f32_32x32x16_bf16 v[80:95], v[176:179], v[116:119], v[80:95]
	ds_read_b128 v[176:179], v184 offset:4096
	ds_read_b128 v[180:183], v184 offset:4608
	s_waitcnt vmcnt(5) lgkmcnt(0)
	v_mfma_f32_32x32x16_bf16 v[64:79], v[180:183], v[120:123], v[64:79]
	v_mfma_f32_32x32x16_bf16 v[80:95], v[176:179], v[120:123], v[80:95]
	ds_read_b128 v[176:179], v184 offset:6144
	ds_read_b128 v[180:183], v184 offset:6656
	v_add_u32_e32 v184, s6, v172
	v_cvt_f32_i32_e32 v199, v184
	s_waitcnt vmcnt(4) lgkmcnt(0)
	v_mfma_f32_32x32x16_bf16 v[64:79], v[180:183], v[124:127], v[64:79]
	v_mfma_f32_32x32x16_bf16 v[80:95], v[176:179], v[124:127], v[80:95]
	v_add_f32_e32 v176, 0xc2000000, v199
	s_nop 9
	v_fma_f32 v64, -v167, |v176|, v64
	v_add_f32_e32 v176, -1.0, v199
	v_exp_f32_e32 v64, v64
	v_fma_f32 v81, -v167, |v176|, v81
	v_add_f32_e32 v176, 0xc2040000, v199
	v_fma_f32 v65, -v167, |v176|, v65
	v_add_f32_e32 v176, -2.0, v199
	v_fma_f32 v82, -v167, |v176|, v82
	v_add_f32_e32 v176, 0xc2080000, v199
	v_fma_f32 v66, -v167, |v176|, v66
	v_add_f32_e32 v176, 0xc0400000, v199
	v_fma_f32 v83, -v167, |v176|, v83
	v_add_f32_e32 v176, 0xc20c0000, v199
	v_fma_f32 v67, -v167, |v176|, v67
	v_add_f32_e32 v176, 0xc1000000, v199
	v_fma_f32 v84, -v167, |v176|, v84
	v_exp_f32_e32 v176, v84
	v_add_f32_e32 v84, 0xc2200000, v199
	v_fma_f32 v68, -v167, |v84|, v68
	v_exp_f32_e32 v178, v68
	v_add_f32_e32 v68, 0xc1100000, v199
	v_fma_f32 v68, -v167, |v68|, v85
	v_exp_f32_e32 v177, v68
	v_add_f32_e32 v68, 0xc2240000, v199
	v_fma_f32 v68, -v167, |v68|, v69
	v_exp_f32_e32 v179, v68
	v_add_f32_e32 v68, 0xc1200000, v199
	v_fma_f32 v68, -v167, |v68|, v86
	v_exp_f32_e32 v180, v68
	v_add_f32_e32 v68, 0xc2280000, v199
	v_fma_f32 v68, -v167, |v68|, v70
	v_exp_f32_e32 v182, v68
	v_add_f32_e32 v68, 0xc1300000, v199
	v_fma_f32 v68, -v167, |v68|, v87
	v_exp_f32_e32 v181, v68
	v_add_f32_e32 v68, 0xc22c0000, v199
	v_fma_f32 v68, -v167, |v68|, v71
	v_exp_f32_e32 v183, v68
	v_add_f32_e32 v68, 0xc1800000, v199
	v_fma_f32 v68, -v167, |v68|, v88
	v_exp_f32_e32 v184, v68
	v_add_f32_e32 v68, 0xc2400000, v199
	v_fma_f32 v68, -v167, |v68|, v72
	v_exp_f32_e32 v186, v68
	v_add_f32_e32 v68, 0xc1880000, v199
	v_fma_f32 v68, -v167, |v68|, v89
	v_exp_f32_e32 v185, v68
	v_add_f32_e32 v68, 0xc2440000, v199
	v_fma_f32 v68, -v167, |v68|, v73
	v_exp_f32_e32 v187, v68
	v_add_f32_e32 v68, 0xc1900000, v199
	v_fma_f32 v68, -v167, |v68|, v90
	v_exp_f32_e32 v188, v68
	v_add_f32_e32 v68, 0xc2480000, v199
	v_fma_f32 v68, -v167, |v68|, v74
	v_exp_f32_e32 v190, v68
	v_add_f32_e32 v68, 0xc1980000, v199
	v_fma_f32 v68, -v167, |v68|, v91
	v_exp_f32_e32 v189, v68
	v_add_f32_e32 v68, 0xc24c0000, v199
	v_fma_f32 v68, -v167, |v68|, v75
	v_exp_f32_e32 v191, v68
	v_add_f32_e32 v68, 0xc1c00000, v199
	v_fma_f32 v68, -v167, |v68|, v92
	v_exp_f32_e32 v192, v68
	v_add_f32_e32 v68, 0xc2600000, v199
	v_fma_f32 v68, -v167, |v68|, v76
	v_exp_f32_e32 v194, v68
	v_add_f32_e32 v68, 0xc1c80000, v199
	v_fma_f32 v68, -v167, |v68|, v93
	v_exp_f32_e32 v193, v68
	v_add_f32_e32 v68, 0xc2640000, v199
	v_fma_f32 v68, -v167, |v68|, v77
	v_exp_f32_e32 v195, v68
	v_add_f32_e32 v68, 0xc1d00000, v199
	v_fma_f32 v80, -v167, |v199|, v80
	v_fma_f32 v68, -v167, |v68|, v94
	v_exp_f32_e32 v80, v80
	v_exp_f32_e32 v81, v81
	v_exp_f32_e32 v82, v82
	v_exp_f32_e32 v83, v83
	v_exp_f32_e32 v196, v68
	v_add_f32_e32 v68, 0xc2680000, v199
	v_fma_f32 v68, -v167, |v68|, v78
	v_exp_f32_e32 v198, v68
	v_add_f32_e32 v68, 0xc1d80000, v199
	v_fma_f32 v68, -v167, |v68|, v95
	v_exp_f32_e32 v197, v68
	v_cvt_pk_bf16_f32 v68, v80, v81
	v_cvt_pk_bf16_f32 v69, v82, v83
	v_cvt_pk_bf16_f32 v70, v176, v177
	v_cvt_pk_bf16_f32 v71, v180, v181
	ds_read_b64_tr_b16 v[72:73], v200 offset:32768
	ds_read_b64_tr_b16 v[74:75], v200 offset:33280
	s_waitcnt lgkmcnt(0)
; #define LAS __attribute__((address_space(3)))
; __device__ __forceinline__ unsigned pk2(float lo, float hi) { f32x2_t v = {lo, hi}; bf16x2_t b = __builtin_convertvector(v, bf16x2_t); return __builtin_bit_cast(unsigned, b); }
; #define MFMA32(a, b, c) __builtin_amdgcn_mfma_f32_32x32x16_bf16((a), (b), (c), 0, 0, 0)
; __device__ __forceinline__ s16x4 vtr(const LAS unsigned char* p) { return __builtin_bit_cast(s16x4, __builtin_amdgcn_ds_read_tr16_b64_v4i16((LAS v4i16_t*)p)); }
; template <int TYPE> __device__ __forceinline__ void attn_unit(const AttnCtx& C, int b, int h, int qb, LAS unsigned char* lds, int tid_in, unsigned* counter) {
;     ...
;                 f32x2_t a2 = {0.f, 0.f};
; #pragma unroll
;                 for (int r = 0; r < 16; r += 2) { a2 += (f32x2_t){p0[r], p0[r + 1]}; a2 += (f32x2_t){p1[r], p1[r + 1]}; }
;                 lsum += a2[0] + a2[1];
;                 bf16x8 pa[4];
; #pragma unroll
;                 for (int s = 0; s < 2; ++s) {
;                     u32x4 a, c2;
;                     a.x = pk2(p0[8 * s + 0], p0[8 * s + 1]); a.y = pk2(p0[8 * s + 2], p0[8 * s + 3]); a.z = pk2(p0[8 * s + 4], p0[8 * s + 5]); a.w = pk2(p0[8 * s + 6], p0[8 * s + 7]);
;                     c2.x = pk2(p1[8 * s + 0], p1[8 * s + 1]); c2.y = pk2(p1[8 * s + 2], p1[8 * s + 3]); c2.z = pk2(p1[8 * s + 4], p1[8 * s + 5]); c2.w = pk2(p1[8 * s + 6], p1[8 * s + 7]);
;                     pa[s] = __builtin_bit_cast(bf16x8, a); pa[2 + s] = __builtin_bit_cast(bf16x8, c2);
;                 }
;                 const LAS unsigned char* vp = Vb + bo + vb0;
; #pragma unroll
;                 for (int dh = 0; dh < 2; ++dh)
; #pragma unroll
;                     for (int ks = 0; ks < 4; ++ks) {
;                         const s16x4 lo = vtr(vp + dh * 4096 + ks * 1024), hh = vtr(vp + dh * 4096 + ks * 1024 + 512);
;                         const bf16x8 vf = {lo[0], lo[1], lo[2], lo[3], hh[0], hh[1], hh[2], hh[3]};
;                         o[dh] = MFMA32(pa[ks], vf, o[dh]);
;                     }
	v_mfma_f32_32x32x16_bf16 v[48:63], v[68:71], v[72:75], v[48:63]
	v_cvt_pk_bf16_f32 v84, v184, v185
	ds_read_b64_tr_b16 v[88:89], v200 offset:33792
	ds_read_b64_tr_b16 v[90:91], v200 offset:34304
	v_cvt_pk_bf16_f32 v85, v188, v189
	v_cvt_pk_bf16_f32 v86, v192, v193
	v_cvt_pk_bf16_f32 v87, v196, v197
	v_exp_f32_e32 v65, v65
	v_exp_f32_e32 v66, v66
	v_exp_f32_e32 v67, v67
	s_waitcnt lgkmcnt(0)
	v_mfma_f32_32x32x16_bf16 v[48:63], v[84:87], v[88:91], v[48:63]
	v_add_f32_e32 v76, 0xc26c0000, v199
	v_fma_f32 v92, -v167, |v76|, v79
	v_cvt_pk_bf16_f32 v72, v64, v65
	v_cvt_pk_bf16_f32 v73, v66, v67
	v_cvt_pk_bf16_f32 v74, v178, v179
	v_cvt_pk_bf16_f32 v75, v182, v183
	ds_read_b64_tr_b16 v[76:77], v200 offset:34816
	ds_read_b64_tr_b16 v[78:79], v200 offset:35328
	v_exp_f32_e32 v199, v92
	s_waitcnt lgkmcnt(0)
	v_mfma_f32_32x32x16_bf16 v[48:63], v[72:75], v[76:79], v[48:63]
	v_cvt_pk_bf16_f32 v88, v186, v187
	ds_read_b64_tr_b16 v[92:93], v200 offset:35840
	ds_read_b64_tr_b16 v[94:95], v200 offset:36352
	v_cvt_pk_bf16_f32 v89, v190, v191
	v_cvt_pk_bf16_f32 v90, v194, v195
	v_cvt_pk_bf16_f32 v91, v198, v199
	s_waitcnt lgkmcnt(0)
	s_nop 0
	v_mfma_f32_32x32x16_bf16 v[48:63], v[88:91], v[92:95], v[48:63]
	ds_read_b64_tr_b16 v[76:77], v200 offset:36864
	ds_read_b64_tr_b16 v[78:79], v200 offset:37376
	ds_read_b64_tr_b16 v[92:93], v200 offset:37888
	ds_read_b64_tr_b16 v[94:95], v200 offset:38400
	s_waitcnt lgkmcnt(2)
	v_mfma_f32_32x32x16_bf16 v[32:47], v[68:71], v[76:79], v[32:47]
	v_add_f32_e64 v68, v80, 0
	v_add_f32_e64 v69, v81, 0
	v_add_f32_e64 v64, v64, v68
	v_add_f32_e64 v65, v65, v69
	v_add_f32_e64 v64, v82, v64
	v_add_f32_e64 v65, v83, v65
	v_pk_add_f32 v[64:65], v[66:67], v[64:65]
	s_waitcnt lgkmcnt(0)
	v_mfma_f32_32x32x16_bf16 v[32:47], v[84:87], v[92:95], v[32:47]
	v_add_f32_e64 v64, v176, v64
	v_add_f32_e64 v65, v177, v65
	v_add_f32_e64 v64, v178, v64
	v_add_f32_e64 v65, v179, v65
	v_add_f32_e64 v64, v180, v64
	v_add_f32_e64 v65, v181, v65
	v_pk_add_f32 v[68:69], v[182:183], v[64:65]
	ds_read_b64_tr_b16 v[64:65], v200 offset:38912
	ds_read_b64_tr_b16 v[66:67], v200 offset:39424
	s_waitcnt lgkmcnt(0)
	v_mfma_f32_32x32x16_bf16 v[32:47], v[72:75], v[64:67], v[32:47]
	v_add_f32_e64 v68, v184, v68
	v_add_f32_e64 v69, v185, v69
	v_add_f32_e64 v76, v186, v68
	v_add_f32_e64 v77, v187, v69
	ds_read_b64_tr_b16 v[68:69], v200 offset:39936
	ds_read_b64_tr_b16 v[70:71], v200 offset:40448
	v_pk_add_f32 v[64:65], v[188:189], v[76:77]
	s_nop 0
	v_pk_add_f32 v[64:65], v[190:191], v[64:65]
	s_waitcnt lgkmcnt(0)
	v_mfma_f32_32x32x16_bf16 v[32:47], v[88:91], v[68:71], v[32:47]
	v_add_f32_e64 v64, v192, v64
	v_add_f32_e64 v65, v193, v65
	v_add_f32_e64 v64, v194, v64
	v_add_f32_e64 v65, v195, v65
	v_add_f32_e64 v64, v196, v64
	v_add_f32_e64 v65, v197, v65
	v_pk_add_f32 v[64:65], v[198:199], v[64:65]
	s_nop 0
	v_add_f32_e32 v64, v64, v65
	v_add_f32_e32 v175, v175, v64
	s_branch .LBB0_445

; __device__ __forceinline__ void xcd_barrier(const XcdBarrier& b, const bool xb_is_leader) {
;     asm volatile("s_waitcnt vmcnt(0)" ::: "memory");
;     __syncthreads();
;     if (xb_is_leader) {
;         unsigned* bar = b.bar;
;         __builtin_amdgcn_s_waitcnt(0);
;         unsigned nloc = b.st[0], nx = b.st[1];
;         if (nloc == 0u) { xcd_barrier_complete(bar, b.x, nloc, nx); b.st[0] = nloc; b.st[1] = nx; }
.LBB0_462:
	s_mov_b32 s0, -1
	s_nop 0
	v_mbcnt_lo_u32_b32 v0, s0, 0
	v_mbcnt_hi_u32_b32 v0, s0, v0
	s_setprio 0
	s_waitcnt vmcnt(0)
	s_waitcnt lgkmcnt(0)
	v_or_b32_e32 v0, s82, v0
	v_cmp_eq_u32_e32 vcc, 0, v0
	s_barrier
	s_and_saveexec_b64 s[4:5], vcc
	v_readlane_b32 s86, v251, 19
	v_readlane_b32 s87, v251, 20
	s_cbranch_execz .LBB0_514
	v_mov_b32_e32 v0, 0x22000
	s_waitcnt vmcnt(0) expcnt(0) lgkmcnt(0)
	ds_read_b32 v2, v0
	v_mov_b32_e32 v0, 0x22004
	ds_read_b32 v0, v0
	s_waitcnt lgkmcnt(1)
	v_cmp_ne_u32_e32 vcc, 0, v2
	s_cbranch_vccnz .LBB0_478
	v_readlane_b32 s0, v251, 0
	v_readlane_b32 s1, v251, 1
	v_readlane_b32 s2, v251, 2
	s_mul_i32 s2, s1, s2
	s_mul_i32 s2, s2, s0
	s_add_u32 s0, s76, 0x1000
	s_addc_u32 s1, s77, 0
	s_add_u32 s6, s76, 0x1100
	s_addc_u32 s7, s77, 0
	s_add_u32 s8, s76, 0x1200
	s_addc_u32 s9, s77, 0
	s_add_u32 s10, s76, 0x1300
	s_addc_u32 s11, s77, 0
	s_mov_b32 s3, 1
	v_mov_b32_e32 v16, 0
	s_branch .LBB0_466

; __device__ __forceinline__ float wave_sum(float v) { return xor32_sum(xor16_sum(row16_sum(v))); }
; #define AIN(i) (kargs()->in[i])
; #define K_TID ((wave_s << 6) | lane_fresh())
; #define K_LANE (lane_fresh())
; __global__ void __launch_bounds__(512, 2) fwd_megakernel(Args a) {
;     ...
;             int lane_l = K_LANE, tid_l = K_TID; asm volatile("" : "+v"(lane_l), "+v"(tid_l));
;             const float* gq = AIN(4) + l * 6 * 64;
;             float mg[6];
; #pragma unroll
;             for (int j = 0; j < 6; ++j) mg[j] = wave_max(fabsf(gq[j * 64 + lane_l]));
;             const float* rel = AIN(8) + l * 6 * 257;
;             float mr = 0.f;
;             for (int i = lane_l; i < 6 * 257; i += 64) mr = fmaxf(mr, fabsf(rel[i]));
;             mr = wave_max(mr);
;             const float* lp = AIN(5) + l * 4 * 64;
;             const float s01 = wave_sum(lp[lane_l] * lp[64 + lane_l]), s23 = wave_sum(lp[128 + lane_l] * lp[192 + lane_l]);
.Lprio_skip_2:
	s_cmp_lg_u32 s98, 0
	s_mov_b32 s0, -1
	v_mbcnt_lo_u32_b32 v0, s1, 0
	v_mbcnt_hi_u32_b32 v0, s1, v0
	s_mov_b64 s[2:3], s[46:47]
	v_mbcnt_lo_u32_b32 v1, s0, 0
	v_mbcnt_hi_u32_b32 v1, s0, v1
	s_mov_b64 s[0:1], s[46:47]
	v_or_b32_e32 v150, s82, v1
	s_load_dwordx2 s[0:1], s[0:1], 0x20
	v_ashrrev_i32_e32 v1, 31, v0
	v_lshlrev_b64 v[0:1], 2, v[0:1]
	v_mov_b32_e32 v8, 0
	v_mov_b32_e32 v12, 0
	s_waitcnt lgkmcnt(0)
	v_lshl_add_u64 v[2:3], s[0:1], 0, v[0:1]
	global_load_dword v4, v[2:3], off offset:1536
	global_load_dword v5, v[2:3], off offset:1792
	global_load_dword v6, v[2:3], off offset:2048
	s_mov_b64 s[0:1], s[46:47]
	global_load_dword v2, v[2:3], off offset:2304
	s_load_dwordx2 s[4:5], s[0:1], 0x40
	s_load_dwordx2 s[0:1], s[2:3], 0x28
	v_mov_b32_e32 v9, 0
	v_mov_b32_e32 v3, 0
	v_mov_b32_e32 v10, 0
	v_mov_b32_e32 v13, 0
	s_waitcnt lgkmcnt(0)
	v_lshl_add_u64 v[0:1], s[0:1], 0, v[0:1]
	global_load_dword v19, v[0:1], off offset:1024
	global_load_dword v20, v[0:1], off offset:1280
	global_load_dword v21, v[0:1], off offset:1536
	global_load_dword v22, v[0:1], off offset:1792
	v_mov_b32_e32 v16, 0
	v_mov_b32_e32 v11, 0
	v_mov_b32_e32 v14, 0
	v_mov_b32_e32 v17, 0
	v_mov_b32_e32 v15, 0
	v_mov_b32_e32 v18, 0
	v_mov_b32_e32 v7, 0
	s_mov_b64 s[0:1], s[46:47]
	s_mov_b32 s8, 0x3fb8aa3b
	s_load_dwordx2 s[0:1], s[0:1], 0x98
	s_mov_b64 s[2:3], s[46:47]
	s_waitcnt lgkmcnt(0)
	v_writelane_b32 v251, s0, 30
	s_nop 1
	v_writelane_b32 v251, s1, 31
	s_mov_b64 s[0:1], s[46:47]
	s_load_dwordx2 s[0:1], s[0:1], 0x98
	s_load_dwordx2 s[6:7], s[2:3], 0x98
	s_mov_b64 s[2:3], s[46:47]
	s_load_dwordx2 s[20:21], s[2:3], 0x30
	s_mov_b32 s2, 0xc2ce8ed0
	s_mov_b32 s3, 0x42b17218
	s_waitcnt vmcnt(7)
	v_and_b32_e32 v0, 0x7fffffff, v4
	s_nop 1
	v_mov_b32_dpp v8, v0 quad_perm:[1,0,3,2] row_mask:0xf bank_mask:0xf
	v_max_f32_e64 v1, |v4|, |v4|
	s_waitcnt vmcnt(6)
	v_and_b32_e32 v4, 0x7fffffff, v5
	v_max_f32_e32 v0, v8, v8
	v_max_f32_e32 v0, v1, v0
	v_mov_b32_dpp v12, v4 quad_perm:[1,0,3,2] row_mask:0xf bank_mask:0xf
	v_max_f32_e64 v5, |v5|, |v5|
	v_max_f32_e32 v4, v12, v12
	v_mov_b32_dpp v9, v0 quad_perm:[2,3,0,1] row_mask:0xf bank_mask:0xf
	s_waitcnt vmcnt(5)
	v_and_b32_e32 v23, 0x7fffffff, v6
	v_max_f32_e32 v1, v5, v4
	v_max_f32_e32 v4, v9, v9
	v_mov_b32_dpp v3, v23 quad_perm:[1,0,3,2] row_mask:0xf bank_mask:0xf
	v_max_f32_e32 v0, v0, v4
	v_max_f32_e64 v6, |v6|, |v6|
	v_max_f32_e32 v3, v3, v3
	v_mov_b32_dpp v10, v0 row_half_mirror row_mask:0xf bank_mask:0xf
	v_max_f32_e32 v3, v6, v3
	v_max_f32_e32 v4, v10, v10
	v_mov_b32_dpp v13, v1 quad_perm:[2,3,0,1] row_mask:0xf bank_mask:0xf
	v_mov_b32_dpp v16, v3 quad_perm:[2,3,0,1] row_mask:0xf bank_mask:0xf
	v_max_f32_e32 v0, v0, v4
	v_max_f32_e32 v5, v13, v13
	v_max_f32_e32 v6, v16, v16
	v_mov_b32_dpp v11, v0 row_mirror row_mask:0xf bank_mask:0xf
	v_max_f32_e32 v1, v1, v5
	v_max_f32_e32 v3, v3, v6
	v_max_f32_e32 v4, v11, v11
	v_mov_b32_dpp v14, v1 row_half_mirror row_mask:0xf bank_mask:0xf
	v_mov_b32_dpp v17, v3 row_half_mirror row_mask:0xf bank_mask:0xf
	v_max_f32_e32 v0, v0, v4
	v_max_f32_e32 v5, v14, v14
	v_max_f32_e32 v6, v17, v17
	v_mov_b32_e32 v4, v0
	v_max_f32_e32 v1, v1, v5
	v_max_f32_e32 v3, v3, v6
	v_permlane16_swap_b32_e32 v0, v4
	v_mov_b32_dpp v15, v1 row_mirror row_mask:0xf bank_mask:0xf
	v_mov_b32_dpp v18, v3 row_mirror row_mask:0xf bank_mask:0xf
	v_max_f32_e32 v4, v4, v4
	v_max_f32_e32 v0, v0, v0
	v_max_f32_e32 v5, v15, v15
	v_max_f32_e32 v6, v18, v18
	v_max_f32_e32 v0, v0, v4
	v_max_f32_e32 v1, v1, v5
	v_max_f32_e32 v3, v3, v6
	v_mov_b32_e32 v4, v0
	v_mov_b32_e32 v5, v1
	v_mov_b32_e32 v6, v3
	v_permlane32_swap_b32_e32 v0, v4
	v_permlane16_swap_b32_e32 v1, v5
	v_max_f32_e32 v4, v4, v4
	v_max_f32_e32 v0, v0, v0
	v_permlane16_swap_b32_e32 v3, v6
	v_max_f32_e32 v5, v5, v5
	v_max_f32_e32 v1, v1, v1
	v_max_f32_e32 v0, v0, v4
	v_max_f32_e32 v4, v6, v6
	v_max_f32_e32 v3, v3, v3
	v_max_f32_e32 v1, v1, v5
	v_max_f32_e32 v3, v3, v4
	v_mov_b32_e32 v5, v1
	v_mov_b32_e32 v4, v3
	s_nop 0
	v_permlane32_swap_b32_e32 v1, v5
	v_permlane32_swap_b32_e32 v3, v4
	v_max_f32_e32 v5, v5, v5
	v_max_f32_e32 v1, v1, v1
	v_max_f32_e32 v4, v4, v4
	v_max_f32_e32 v3, v3, v3
	v_max_f32_e32 v1, v1, v5
	v_max_f32_e32 v3, v3, v4
	s_waitcnt vmcnt(4)
; #define LAS __attribute__((address_space(3)))
; __device__ __forceinline__ float wave_sum(float v) { return xor32_sum(xor16_sum(row16_sum(v))); }
; #define AIN(i) (kargs()->in[i])
; #define AWS (kargs()->ws)
;             #define RFL(x) __uint_as_float(__builtin_amdgcn_readfirstlane(__float_as_uint(x)))
; __device__ __forceinline__ void attn_phase(const AttnCtx& C, unsigned* counter, LAS unsigned char* lds, int tid) {
;     LAS unsigned* ub = (LAS unsigned*)(lds + AL_U);
;     __syncthreads();
;     if (tid == 0) ub[0] = atomicAdd(counter, 1u);
; __global__ void __launch_bounds__(512, 2) fwd_megakernel(Args a) {
;     ...
;             for (int j = 0; j < 6; ++j) mg[j] = wave_max(fabsf(gq[j * 64 + lane_l]));
;             const float* rel = AIN(8) + l * 6 * 257;
;             float mr = 0.f;
;             for (int i = lane_l; i < 6 * 257; i += 64) mr = fmaxf(mr, fabsf(rel[i]));
;             mr = wave_max(mr);
;             const float* lp = AIN(5) + l * 4 * 64;
;             const float s01 = wave_sum(lp[lane_l] * lp[64 + lane_l]), s23 = wave_sum(lp[128 + lane_l] * lp[192 + lane_l]);
;             const float lam_init = (l == 0) ? 0.2f : (0.8f - 0.6f * 0.7408182206817179f);
;             AttnCtx C;
;             C.Z = P_Zb; C.O = P_HN; C.F2 = P_F2; C.rel = rel; C.subln = AIN(6) + l * 64;
;             C.lam = expf(s01) - expf(s23) + lam_init; C.oml = 1.0f - lam_init;
;             C.Mb0 = 8.0f * mg[0] * mg[1] * LOG2E * 1.02f + 1.0f; C.Mb1 = 8.0f * mg[2] * mg[3] * LOG2E * 1.02f + 1.0f; C.Mb2 = 8.0f * mg[4] * mg[5] * LOG2E * 1.02f + 1.0f + mr * LOG2E;
;     ...
;             C.lam = RFL(C.lam); C.oml = RFL(C.oml); C.Mb0 = RFL(C.Mb0); C.Mb1 = RFL(C.Mb1); C.Mb2 = RFL(C.Mb2);
;             attn_phase(C, (unsigned*)(AWS + WS_CTL) + CTL_Q + 16 * (1 + l), lds, tid_l);
	v_and_b32_e32 v4, 0x7fffffff, v2
	v_mov_b32_e32 v5, 0
	v_max_f32_e64 v2, |v2|, |v2|
	v_mul_f32_e32 v0, 0x41000000, v0
	v_mov_b32_dpp v5, v4 quad_perm:[1,0,3,2] row_mask:0xf bank_mask:0xf
	v_max_f32_e32 v4, v5, v5
	v_max_f32_e32 v2, v2, v4
	v_mov_b32_e32 v4, 0
	v_mov_b32_e32 v5, 0
	v_mul_f32_e32 v0, v0, v1
	v_mov_b32_dpp v4, v2 quad_perm:[2,3,0,1] row_mask:0xf bank_mask:0xf
	v_max_f32_e32 v4, v4, v4
	v_max_f32_e32 v2, v2, v4
	v_mov_b32_e32 v4, 0
	v_mul_f32_e32 v1, 0x41000000, v3
	v_readfirstlane_b32 s13, v0
	v_mov_b32_dpp v4, v2 row_half_mirror row_mask:0xf bank_mask:0xf
	v_max_f32_e32 v4, v4, v4
	v_max_f32_e32 v2, v2, v4
	v_mov_b32_e32 v4, 0
	s_nop 1
	v_mov_b32_dpp v4, v2 row_mirror row_mask:0xf bank_mask:0xf
	v_max_f32_e32 v4, v4, v4
	v_max_f32_e32 v2, v2, v4
	v_mov_b32_e32 v4, v2
	s_nop 1
	v_permlane16_swap_b32_e32 v2, v4
	v_max_f32_e32 v4, v4, v4
	v_max_f32_e32 v2, v2, v2
	v_max_f32_e32 v2, v2, v4
	v_mov_b32_e32 v4, v2
	s_nop 1
	v_permlane32_swap_b32_e32 v2, v4
	v_max_f32_e32 v4, v4, v4
	v_max_f32_e32 v2, v2, v2
	v_max_f32_e32 v2, v2, v4
	s_waitcnt vmcnt(2)
	v_mul_f32_e32 v4, v19, v20
	v_mul_f32_e32 v1, v1, v2
	s_nop 0
	v_mov_b32_dpp v5, v4 quad_perm:[1,0,3,2] row_mask:0xf bank_mask:0xf
	v_fmac_f32_e32 v5, v19, v20
	v_readfirstlane_b32 s12, v1
	s_nop 0
	v_add_f32_dpp v4, v5, v5 quad_perm:[2,3,0,1] row_mask:0xf bank_mask:0xf bound_ctrl:1
	s_nop 1
	v_add_f32_dpp v4, v4, v4 row_half_mirror row_mask:0xf bank_mask:0xf bound_ctrl:1
	s_nop 1
	v_add_f32_dpp v4, v4, v4 row_mirror row_mask:0xf bank_mask:0xf bound_ctrl:1
	v_mov_b32_e32 v5, v4
	s_nop 1
	v_permlane16_swap_b32_e32 v4, v5
	v_add_f32_e32 v4, v4, v5
	v_mov_b32_e32 v5, v4
	s_nop 1
	v_permlane32_swap_b32_e32 v4, v5
	v_add_f32_e32 v4, v4, v5
	s_waitcnt vmcnt(0)
	v_mul_f32_e32 v5, v21, v22
	v_cmp_ngt_f32_e32 vcc, s2, v4
	s_nop 0
	v_mov_b32_dpp v7, v5 quad_perm:[1,0,3,2] row_mask:0xf bank_mask:0xf
	v_fmac_f32_e32 v7, v21, v22
	s_nop 1
	v_add_f32_dpp v5, v7, v7 quad_perm:[2,3,0,1] row_mask:0xf bank_mask:0xf bound_ctrl:1
	s_nop 1
	v_add_f32_dpp v5, v5, v5 row_half_mirror row_mask:0xf bank_mask:0xf bound_ctrl:1
	s_nop 1
	v_add_f32_dpp v5, v5, v5 row_mirror row_mask:0xf bank_mask:0xf bound_ctrl:1
	v_mov_b32_e32 v6, v5
	s_nop 1
	v_permlane16_swap_b32_e32 v5, v6
	v_add_f32_e32 v5, v5, v6
	v_mov_b32_e32 v6, v5
	s_nop 1
	v_permlane32_swap_b32_e32 v5, v6
	v_add_f32_e32 v5, v5, v6
	v_mul_f32_e32 v6, 0x3fb8aa3b, v4
	v_fma_f32 v7, v4, s8, -v6
	v_rndne_f32_e32 v8, v6
	v_fmac_f32_e32 v7, 0x32a5705f, v4
	v_sub_f32_e32 v6, v6, v8
	v_add_f32_e32 v6, v6, v7
	v_exp_f32_e32 v6, v6
	v_cvt_i32_f32_e32 v7, v8
	v_ldexp_f32 v6, v6, v7
	v_mul_f32_e32 v7, 0x3fb8aa3b, v5
	v_fma_f32 v8, v5, s8, -v7
	v_rndne_f32_e32 v9, v7
	v_fmac_f32_e32 v8, 0x32a5705f, v5
	v_sub_f32_e32 v7, v7, v9
	v_add_f32_e32 v7, v7, v8
	v_exp_f32_e32 v7, v7
	v_cvt_i32_f32_e32 v8, v9
	v_cndmask_b32_e32 v6, 0, v6, vcc
	v_mov_b32_e32 v9, 0x7f800000
	v_cmp_nlt_f32_e32 vcc, s3, v4
	s_nop 1
	v_cndmask_b32_e32 v4, v9, v6, vcc
	v_ldexp_f32 v6, v7, v8
	v_cmp_ngt_f32_e32 vcc, s2, v5
	s_nop 1
	v_cndmask_b32_e32 v6, 0, v6, vcc
	v_cmp_nlt_f32_e32 vcc, s3, v5
	s_mov_b64 s[2:3], s[46:47]
	s_load_dwordx2 s[2:3], s[2:3], 0x98
	v_cndmask_b32_e32 v5, v9, v6, vcc
	v_sub_f32_e32 v4, v4, v5
	v_cmp_eq_u32_e32 vcc, 0, v150
	v_readfirstlane_b32 s14, v4
	s_waitcnt lgkmcnt(0)
	s_add_u32 s2, s2, 0x3880
	s_addc_u32 s3, s3, 0
	v_writelane_b32 v251, s2, 17
	s_barrier
	s_nop 0
	v_writelane_b32 v251, s3, 18
	s_and_saveexec_b64 s[8:9], vcc
	s_cbranch_execz .LBB0_1275
	s_mov_b64 s[2:3], exec
	v_mbcnt_lo_u32_b32 v0, s2, 0
	v_mbcnt_hi_u32_b32 v0, s3, v0
	v_cmp_eq_u32_e32 vcc, 0, v0
	s_and_saveexec_b64 s[10:11], vcc
	s_cbranch_execz .LBB0_1274
	s_bcnt1_i32_b64 s2, s[2:3]
	v_mov_b32_e32 v2, s2
	v_readlane_b32 s2, v251, 17
	v_mov_b32_e32 v1, 0
	v_readlane_b32 s3, v251, 18
	s_nop 4
	global_atomic_add v1, v1, v2, s[2:3] sc0

; template <int TYPE> __device__ __forceinline__ void attn_unit(const AttnCtx& C, int b, int h, int qb, LAS unsigned char* lds, int tid_in, unsigned* counter) {
;     ...
;             const bool active = (TYPE == 2) ? (t >= cq - 8 && t <= cq) : (TYPE == 0) ? (t <= cq && (float)(256 * qb + 32 * w - 64 * t - 63) < dmax) : (t <= cq && t >= tfirst);
;             if (active) {
;                 f32x16 p0, p1;
;                 const LAS unsigned char* kp = Kb + bo + hi * 1024 + r32 * 16;
; #pragma unroll
;                 for (int d0 = 0; d0 < 4; ++d0) {
;                     const bf16x8 a0 = *(const LAS bf16x8*)(kp + d0 * 2048), a1 = *(const LAS bf16x8*)(kp + d0 * 2048 + 512);
;                     if (d0 == 0) { p0 = MFMA32(a0, qr[0], (TYPE == 1 ? cvec : zvec)); p1 = MFMA32(a1, qr[0], (TYPE == 1 ? cvec : zvec)); }
;                     else { p0 = MFMA32(a0, qr[d0], p0); p1 = MFMA32(a1, qr[d0], p1); }
;                 }
;                 const int xi = sq - 64 * t - 4 * hi;
;                 if (TYPE == 0) {
;                     const float xf = (float)xi;
; #pragma unroll
;                     for (int r = 0; r < 16; ++r) { const float c = (float)((r & 3) + 8 * (r >> 2));
;                         p0[r] = fast_exp2(p0[r] - sl2 * fabsf(xf - c)); p1[r] = fast_exp2(p1[r] - sl2 * fabsf(xf - (c + 32.f))); }
;                 } else if (TYPE == 1) {
;                     const LAS float* fp = Fb + (t & 3) * 64 + 4 * hi;
; #pragma unroll
;                     for (int g = 0; g < 4; ++g) { const f32x4 fa = *(const LAS f32x4*)(fp + 8 * g), fb2 = *(const LAS f32x4*)(fp + 32 + 8 * g);
; #pragma unroll
;                         for (int i = 0; i < 4; i += 2) {
;                             const f32x2_t d0_ = (f32x2_t){p0[4 * g + i], p0[4 * g + i + 1]} - (f32x2_t){fa[i], fa[i + 1]}, d1_ = (f32x2_t){p1[4 * g + i], p1[4 * g + i + 1]} - (f32x2_t){fb2[i], fb2[i + 1]};
;                             p0[4 * g + i] = fast_exp2(d0_[0]); p0[4 * g + i + 1] = fast_exp2(d0_[1]); p1[4 * g + i] = fast_exp2(d1_[0]); p1[4 * g + i + 1] = fast_exp2(d1_[1]); } }
;                     if (t == cq) { const int qrel = 32 * (w & 1) + r32;
; #pragma unroll
;                         for (int r = 0; r < 16; ++r) { const int kv = crow(r, hi); if (kv > qrel) p0[r] = 0.f; if (kv + 32 > qrel) p1[r] = 0.f; } }
;                 } else {
;                     if (cq - t >= 3) { const float bc = relb[256];
.LBB0_1364:
	s_cmp_gt_i32 s3, s12
	s_cbranch_scc1 .LBB0_1359
	s_sub_i32 s7, s0, 63
	v_cvt_f32_i32_e32 v32, s7
	v_cmp_ngt_f32_e32 vcc, v168, v32
	s_cbranch_vccnz .LBB0_1359
	s_cmp_eq_u32 s3, s12
	s_cbranch_scc1 .Lt0diag_2
	v_add_u32_e32 v118, s6, v171
	v_add_u32_e32 v213, s0, v172
	v_cvt_f32_i32_e32 v213, v213
	v_mul_f32_e64 v210, -v167, v213
	ds_read_b128 v[202:205], v118
	ds_read_b128 v[206:209], v118 offset:512
	ds_read_b128 v[110:113], v118 offset:2048
	ds_read_b128 v[114:117], v118 offset:2560
	v_add_u32_e32 v134, s6, v170
	v_mov_b32_e32 v48, v210
	v_fmamk_f32 v49, v167, 0x3f800000, v210
	v_fmamk_f32 v50, v167, 0x40000000, v210
	v_fmamk_f32 v51, v167, 0x40400000, v210
	v_fmamk_f32 v52, v167, 0x41000000, v210
	v_fmamk_f32 v53, v167, 0x41100000, v210
	v_fmamk_f32 v54, v167, 0x41200000, v210
	v_fmamk_f32 v55, v167, 0x41300000, v210
	v_fmamk_f32 v56, v167, 0x41800000, v210
	v_fmamk_f32 v57, v167, 0x41880000, v210
	v_fmamk_f32 v58, v167, 0x41900000, v210
	v_fmamk_f32 v59, v167, 0x41980000, v210
	v_fmamk_f32 v60, v167, 0x41c00000, v210
	v_fmamk_f32 v61, v167, 0x41c80000, v210
	v_fmamk_f32 v62, v167, 0x41d00000, v210
	v_fmamk_f32 v63, v167, 0x41d80000, v210
	v_fmamk_f32 v32, v167, 0x42000000, v210
	v_fmamk_f32 v33, v167, 0x42040000, v210
	v_fmamk_f32 v34, v167, 0x42080000, v210
	v_fmamk_f32 v35, v167, 0x420c0000, v210
	v_fmamk_f32 v36, v167, 0x42200000, v210
	v_fmamk_f32 v37, v167, 0x42240000, v210
	v_fmamk_f32 v38, v167, 0x42280000, v210
	v_fmamk_f32 v39, v167, 0x422c0000, v210
	v_fmamk_f32 v40, v167, 0x42400000, v210
	v_fmamk_f32 v41, v167, 0x42440000, v210
	v_fmamk_f32 v42, v167, 0x42480000, v210
	v_fmamk_f32 v43, v167, 0x424c0000, v210
	v_fmamk_f32 v44, v167, 0x42600000, v210
	v_fmamk_f32 v45, v167, 0x42640000, v210
	v_fmamk_f32 v46, v167, 0x42680000, v210
	v_fmamk_f32 v47, v167, 0x426c0000, v210
	s_waitcnt vmcnt(7) lgkmcnt(3)
	v_mfma_f32_32x32x16_bf16 v[48:63], v[202:205], v[64:67], v[48:63]
	s_waitcnt lgkmcnt(2)
	v_mfma_f32_32x32x16_bf16 v[32:47], v[206:209], v[64:67], v[32:47]
	s_waitcnt vmcnt(6) lgkmcnt(0)
	v_mfma_f32_32x32x16_bf16 v[32:47], v[114:117], v[68:71], v[32:47]
	v_mfma_f32_32x32x16_bf16 v[48:63], v[110:113], v[68:71], v[48:63]
	ds_read_b128 v[110:113], v118 offset:4096
	ds_read_b128 v[114:117], v118 offset:4608
	s_waitcnt vmcnt(5) lgkmcnt(0)
	v_mfma_f32_32x32x16_bf16 v[32:47], v[114:117], v[72:75], v[32:47]
	v_mfma_f32_32x32x16_bf16 v[48:63], v[110:113], v[72:75], v[48:63]
	ds_read_b128 v[110:113], v118 offset:6144
	ds_read_b128 v[114:117], v118 offset:6656
	s_waitcnt vmcnt(4) lgkmcnt(0)
	v_mfma_f32_32x32x16_bf16 v[32:47], v[114:117], v[76:79], v[32:47]
	v_mfma_f32_32x32x16_bf16 v[48:63], v[110:113], v[76:79], v[48:63]
	s_nop 11
	v_exp_f32_e32 v32, v32
	v_exp_f32_e32 v110, v52
	v_exp_f32_e32 v112, v36
	v_exp_f32_e32 v111, v53
	v_exp_f32_e32 v113, v37
	v_exp_f32_e32 v114, v54
	v_exp_f32_e32 v116, v38
	v_exp_f32_e32 v115, v55
	v_exp_f32_e32 v117, v39
	v_exp_f32_e32 v118, v56
	v_exp_f32_e32 v120, v40
	v_exp_f32_e32 v119, v57
	v_exp_f32_e32 v121, v41
	v_exp_f32_e32 v122, v58
	v_exp_f32_e32 v124, v42
	v_exp_f32_e32 v123, v59
	v_exp_f32_e32 v125, v43
	v_exp_f32_e32 v126, v60
	v_exp_f32_e32 v128, v44
	v_exp_f32_e32 v127, v61
	v_exp_f32_e32 v129, v45
	v_exp_f32_e32 v48, v48
	v_exp_f32_e32 v49, v49
	v_exp_f32_e32 v50, v50
	v_exp_f32_e32 v51, v51
	v_exp_f32_e32 v130, v62
	v_exp_f32_e32 v132, v46
	v_exp_f32_e32 v131, v63
	v_cvt_pk_bf16_f32 v36, v48, v49
	v_cvt_pk_bf16_f32 v37, v50, v51
	v_cvt_pk_bf16_f32 v38, v110, v111
	v_cvt_pk_bf16_f32 v39, v114, v115
	ds_read_b64_tr_b16 v[40:41], v134 offset:32768
	ds_read_b64_tr_b16 v[42:43], v134 offset:33280
	s_waitcnt lgkmcnt(0)
	v_mfma_f32_32x32x16_bf16 v[16:31], v[36:39], v[40:43], v[16:31]
	v_cvt_pk_bf16_f32 v52, v118, v119
	ds_read_b64_tr_b16 v[56:57], v134 offset:33792
	ds_read_b64_tr_b16 v[58:59], v134 offset:34304
	v_cvt_pk_bf16_f32 v53, v122, v123
	v_cvt_pk_bf16_f32 v54, v126, v127
	v_cvt_pk_bf16_f32 v55, v130, v131
	v_exp_f32_e32 v33, v33
	v_exp_f32_e32 v34, v34
	v_exp_f32_e32 v35, v35
	s_waitcnt lgkmcnt(0)
	v_mfma_f32_32x32x16_bf16 v[16:31], v[52:55], v[56:59], v[16:31]
	v_exp_f32_e32 v133, v47
	v_cvt_pk_bf16_f32 v40, v32, v33
	v_cvt_pk_bf16_f32 v41, v34, v35
	v_cvt_pk_bf16_f32 v42, v112, v113
	v_cvt_pk_bf16_f32 v43, v116, v117
	ds_read_b64_tr_b16 v[44:45], v134 offset:34816
	ds_read_b64_tr_b16 v[46:47], v134 offset:35328
	s_waitcnt lgkmcnt(0)
	v_mfma_f32_32x32x16_bf16 v[16:31], v[40:43], v[44:47], v[16:31]
	v_cvt_pk_bf16_f32 v56, v120, v121
	ds_read_b64_tr_b16 v[60:61], v134 offset:35840
	ds_read_b64_tr_b16 v[62:63], v134 offset:36352
	v_cvt_pk_bf16_f32 v57, v124, v125
	v_cvt_pk_bf16_f32 v58, v128, v129
	v_cvt_pk_bf16_f32 v59, v132, v133
	s_waitcnt lgkmcnt(0)
	s_nop 0
	v_mfma_f32_32x32x16_bf16 v[16:31], v[56:59], v[60:63], v[16:31]
	ds_read_b64_tr_b16 v[44:45], v134 offset:36864
	ds_read_b64_tr_b16 v[46:47], v134 offset:37376
	ds_read_b64_tr_b16 v[60:61], v134 offset:37888
	ds_read_b64_tr_b16 v[62:63], v134 offset:38400
	s_waitcnt lgkmcnt(2)
	v_mfma_f32_32x32x16_bf16 v[0:15], v[36:39], v[44:47], v[0:15]
	v_add_f32_e64 v36, v48, 0
	v_add_f32_e64 v37, v49, 0
	v_add_f32_e64 v32, v32, v36
	v_add_f32_e64 v33, v33, v37
	v_add_f32_e64 v32, v50, v32
	v_add_f32_e64 v33, v51, v33
	v_pk_add_f32 v[32:33], v[34:35], v[32:33]
	s_waitcnt lgkmcnt(0)
	v_mfma_f32_32x32x16_bf16 v[0:15], v[52:55], v[60:63], v[0:15]
	v_add_f32_e64 v32, v110, v32
	v_add_f32_e64 v33, v111, v33
	v_add_f32_e64 v32, v112, v32
	v_add_f32_e64 v33, v113, v33
	v_add_f32_e64 v32, v114, v32
	v_add_f32_e64 v33, v115, v33
	v_pk_add_f32 v[36:37], v[116:117], v[32:33]
	ds_read_b64_tr_b16 v[32:33], v134 offset:38912
	ds_read_b64_tr_b16 v[34:35], v134 offset:39424
	s_waitcnt lgkmcnt(0)
	v_mfma_f32_32x32x16_bf16 v[0:15], v[40:43], v[32:35], v[0:15]
	v_add_f32_e64 v36, v118, v36
	v_add_f32_e64 v37, v119, v37
	v_add_f32_e64 v44, v120, v36
	v_add_f32_e64 v45, v121, v37
	ds_read_b64_tr_b16 v[36:37], v134 offset:39936
	ds_read_b64_tr_b16 v[38:39], v134 offset:40448
	v_pk_add_f32 v[32:33], v[122:123], v[44:45]
	s_nop 0
	v_pk_add_f32 v[32:33], v[124:125], v[32:33]
	s_waitcnt lgkmcnt(0)
	v_mfma_f32_32x32x16_bf16 v[0:15], v[56:59], v[36:39], v[0:15]
	v_add_f32_e64 v32, v126, v32
	v_add_f32_e64 v33, v127, v33
	v_add_f32_e64 v32, v128, v32
	v_add_f32_e64 v33, v129, v33
	v_add_f32_e64 v32, v130, v32
	v_add_f32_e64 v33, v131, v33
	v_pk_add_f32 v[32:33], v[132:133], v[32:33]
	s_nop 0
	v_add_f32_e32 v32, v32, v33
	v_add_f32_e32 v109, v109, v32
	s_branch .LBB0_1359
; #define LAS __attribute__((address_space(3)))
; __device__ __forceinline__ float fast_exp2(float x) { return __builtin_amdgcn_exp2f(x); }
; #define MFMA32(a, b, c) __builtin_amdgcn_mfma_f32_32x32x16_bf16((a), (b), (c), 0, 0, 0)
; template <int TYPE> __device__ __forceinline__ void attn_unit(const AttnCtx& C, int b, int h, int qb, LAS unsigned char* lds, int tid_in, unsigned* counter) {
;     ...
;                 f32x16 p0, p1;
;                 const LAS unsigned char* kp = Kb + bo + hi * 1024 + r32 * 16;
; #pragma unroll
;                 for (int d0 = 0; d0 < 4; ++d0) {
;                     const bf16x8 a0 = *(const LAS bf16x8*)(kp + d0 * 2048), a1 = *(const LAS bf16x8*)(kp + d0 * 2048 + 512);
;                     if (d0 == 0) { p0 = MFMA32(a0, qr[0], (TYPE == 1 ? cvec : zvec)); p1 = MFMA32(a1, qr[0], (TYPE == 1 ? cvec : zvec)); }
;                     else { p0 = MFMA32(a0, qr[d0], p0); p1 = MFMA32(a1, qr[d0], p1); }
;                 }
;                 const int xi = sq - 64 * t - 4 * hi;
;                 if (TYPE == 0) {
;                     const float xf = (float)xi;
; #pragma unroll
;                     for (int r = 0; r < 16; ++r) { const float c = (float)((r & 3) + 8 * (r >> 2));
;                         p0[r] = fast_exp2(p0[r] - sl2 * fabsf(xf - c)); p1[r] = fast_exp2(p1[r] - sl2 * fabsf(xf - (c + 32.f))); }
.Lt0diag_2:
	v_add_u32_e32 v118, s6, v171
	ds_read_b128 v[32:35], v118
	ds_read_b128 v[36:39], v118 offset:512
	ds_read_b128 v[110:113], v118 offset:2048
	ds_read_b128 v[114:117], v118 offset:2560
	v_add_u32_e32 v134, s6, v170
	s_waitcnt vmcnt(7) lgkmcnt(3)
	v_mfma_f32_32x32x16_bf16 v[48:63], v[32:35], v[64:67], 0
	s_waitcnt lgkmcnt(2)
	v_mfma_f32_32x32x16_bf16 v[32:47], v[36:39], v[64:67], 0
	s_waitcnt vmcnt(6) lgkmcnt(0)
	v_mfma_f32_32x32x16_bf16 v[32:47], v[114:117], v[68:71], v[32:47]
	v_mfma_f32_32x32x16_bf16 v[48:63], v[110:113], v[68:71], v[48:63]
	ds_read_b128 v[110:113], v118 offset:4096
	ds_read_b128 v[114:117], v118 offset:4608
	s_waitcnt vmcnt(5) lgkmcnt(0)
	v_mfma_f32_32x32x16_bf16 v[32:47], v[114:117], v[72:75], v[32:47]
	v_mfma_f32_32x32x16_bf16 v[48:63], v[110:113], v[72:75], v[48:63]
	ds_read_b128 v[110:113], v118 offset:6144
	ds_read_b128 v[114:117], v118 offset:6656
	v_add_u32_e32 v118, s0, v172
	v_cvt_f32_i32_e32 v133, v118
	s_waitcnt vmcnt(4) lgkmcnt(0)
	v_mfma_f32_32x32x16_bf16 v[32:47], v[114:117], v[76:79], v[32:47]
	v_mfma_f32_32x32x16_bf16 v[48:63], v[110:113], v[76:79], v[48:63]
	v_add_f32_e32 v110, 0xc2000000, v133
	s_nop 9
	v_fma_f32 v32, -v167, |v110|, v32
	v_add_f32_e32 v110, -1.0, v133
	v_exp_f32_e32 v32, v32
	v_fma_f32 v49, -v167, |v110|, v49
	v_add_f32_e32 v110, 0xc2040000, v133
	v_fma_f32 v33, -v167, |v110|, v33
	v_add_f32_e32 v110, -2.0, v133
	v_fma_f32 v50, -v167, |v110|, v50
	v_add_f32_e32 v110, 0xc2080000, v133
	v_fma_f32 v34, -v167, |v110|, v34
	v_add_f32_e32 v110, 0xc0400000, v133
	v_fma_f32 v51, -v167, |v110|, v51
	v_add_f32_e32 v110, 0xc20c0000, v133
	v_fma_f32 v35, -v167, |v110|, v35
	v_add_f32_e32 v110, 0xc1000000, v133
	v_fma_f32 v52, -v167, |v110|, v52
	v_exp_f32_e32 v110, v52
	v_add_f32_e32 v52, 0xc2200000, v133
	v_fma_f32 v36, -v167, |v52|, v36
	v_exp_f32_e32 v112, v36
	v_add_f32_e32 v36, 0xc1100000, v133
	v_fma_f32 v36, -v167, |v36|, v53
	v_exp_f32_e32 v111, v36
	v_add_f32_e32 v36, 0xc2240000, v133
	v_fma_f32 v36, -v167, |v36|, v37
	v_exp_f32_e32 v113, v36
	v_add_f32_e32 v36, 0xc1200000, v133
	v_fma_f32 v36, -v167, |v36|, v54
	v_exp_f32_e32 v114, v36
	v_add_f32_e32 v36, 0xc2280000, v133
	v_fma_f32 v36, -v167, |v36|, v38
	v_exp_f32_e32 v116, v36
	v_add_f32_e32 v36, 0xc1300000, v133
	v_fma_f32 v36, -v167, |v36|, v55
	v_exp_f32_e32 v115, v36
	v_add_f32_e32 v36, 0xc22c0000, v133
	v_fma_f32 v36, -v167, |v36|, v39
	v_exp_f32_e32 v117, v36
	v_add_f32_e32 v36, 0xc1800000, v133
	v_fma_f32 v36, -v167, |v36|, v56
	v_exp_f32_e32 v118, v36
	v_add_f32_e32 v36, 0xc2400000, v133
	v_fma_f32 v36, -v167, |v36|, v40
	v_exp_f32_e32 v120, v36
	v_add_f32_e32 v36, 0xc1880000, v133
	v_fma_f32 v36, -v167, |v36|, v57
	v_exp_f32_e32 v119, v36
	v_add_f32_e32 v36, 0xc2440000, v133
	v_fma_f32 v36, -v167, |v36|, v41
	v_exp_f32_e32 v121, v36
	v_add_f32_e32 v36, 0xc1900000, v133
	v_fma_f32 v36, -v167, |v36|, v58
	v_exp_f32_e32 v122, v36
	v_add_f32_e32 v36, 0xc2480000, v133
	v_fma_f32 v36, -v167, |v36|, v42
	v_exp_f32_e32 v124, v36
	v_add_f32_e32 v36, 0xc1980000, v133
	v_fma_f32 v36, -v167, |v36|, v59
	v_exp_f32_e32 v123, v36
	v_add_f32_e32 v36, 0xc24c0000, v133
	v_fma_f32 v36, -v167, |v36|, v43
	v_exp_f32_e32 v125, v36
	v_add_f32_e32 v36, 0xc1c00000, v133
	v_fma_f32 v36, -v167, |v36|, v60
	v_exp_f32_e32 v126, v36
	v_add_f32_e32 v36, 0xc2600000, v133
	v_fma_f32 v36, -v167, |v36|, v44
	v_exp_f32_e32 v128, v36
	v_add_f32_e32 v36, 0xc1c80000, v133
	v_fma_f32 v36, -v167, |v36|, v61
	v_exp_f32_e32 v127, v36
	v_add_f32_e32 v36, 0xc2640000, v133
	v_fma_f32 v36, -v167, |v36|, v45
	v_exp_f32_e32 v129, v36
	v_add_f32_e32 v36, 0xc1d00000, v133
	v_fma_f32 v48, -v167, |v133|, v48
	v_fma_f32 v36, -v167, |v36|, v62
	v_exp_f32_e32 v48, v48
	v_exp_f32_e32 v49, v49
	v_exp_f32_e32 v50, v50
	v_exp_f32_e32 v51, v51
	v_exp_f32_e32 v130, v36
	v_add_f32_e32 v36, 0xc2680000, v133
	v_fma_f32 v36, -v167, |v36|, v46
	v_exp_f32_e32 v132, v36
	v_add_f32_e32 v36, 0xc1d80000, v133
	v_fma_f32 v36, -v167, |v36|, v63
	v_exp_f32_e32 v131, v36
	v_cvt_pk_bf16_f32 v36, v48, v49
	v_cvt_pk_bf16_f32 v37, v50, v51
	v_cvt_pk_bf16_f32 v38, v110, v111
	v_cvt_pk_bf16_f32 v39, v114, v115
	ds_read_b64_tr_b16 v[40:41], v134 offset:32768
	ds_read_b64_tr_b16 v[42:43], v134 offset:33280
	s_waitcnt lgkmcnt(0)
; #define LAS __attribute__((address_space(3)))
; __device__ __forceinline__ unsigned pk2(float lo, float hi) { f32x2_t v = {lo, hi}; bf16x2_t b = __builtin_convertvector(v, bf16x2_t); return __builtin_bit_cast(unsigned, b); }
; #define MFMA32(a, b, c) __builtin_amdgcn_mfma_f32_32x32x16_bf16((a), (b), (c), 0, 0, 0)
; __device__ __forceinline__ s16x4 vtr(const LAS unsigned char* p) { return __builtin_bit_cast(s16x4, __builtin_amdgcn_ds_read_tr16_b64_v4i16((LAS v4i16_t*)p)); }
; template <int TYPE> __device__ __forceinline__ void attn_unit(const AttnCtx& C, int b, int h, int qb, LAS unsigned char* lds, int tid_in, unsigned* counter) {
;     ...
;                 f32x2_t a2 = {0.f, 0.f};
; #pragma unroll
;                 for (int r = 0; r < 16; r += 2) { a2 += (f32x2_t){p0[r], p0[r + 1]}; a2 += (f32x2_t){p1[r], p1[r + 1]}; }
;                 lsum += a2[0] + a2[1];
;                 bf16x8 pa[4];
; #pragma unroll
;                 for (int s = 0; s < 2; ++s) {
;                     u32x4 a, c2;
;                     a.x = pk2(p0[8 * s + 0], p0[8 * s + 1]); a.y = pk2(p0[8 * s + 2], p0[8 * s + 3]); a.z = pk2(p0[8 * s + 4], p0[8 * s + 5]); a.w = pk2(p0[8 * s + 6], p0[8 * s + 7]);
;                     c2.x = pk2(p1[8 * s + 0], p1[8 * s + 1]); c2.y = pk2(p1[8 * s + 2], p1[8 * s + 3]); c2.z = pk2(p1[8 * s + 4], p1[8 * s + 5]); c2.w = pk2(p1[8 * s + 6], p1[8 * s + 7]);
;                     pa[s] = __builtin_bit_cast(bf16x8, a); pa[2 + s] = __builtin_bit_cast(bf16x8, c2);
;                 }
;                 const LAS unsigned char* vp = Vb + bo + vb0;
; #pragma unroll
;                 for (int dh = 0; dh < 2; ++dh)
; #pragma unroll
;                     for (int ks = 0; ks < 4; ++ks) {
;                         const s16x4 lo = vtr(vp + dh * 4096 + ks * 1024), hh = vtr(vp + dh * 4096 + ks * 1024 + 512);
;                         const bf16x8 vf = {lo[0], lo[1], lo[2], lo[3], hh[0], hh[1], hh[2], hh[3]};
;                         o[dh] = MFMA32(pa[ks], vf, o[dh]);
;                     }
	v_mfma_f32_32x32x16_bf16 v[16:31], v[36:39], v[40:43], v[16:31]
	v_cvt_pk_bf16_f32 v52, v118, v119
	ds_read_b64_tr_b16 v[56:57], v134 offset:33792
	ds_read_b64_tr_b16 v[58:59], v134 offset:34304
	v_cvt_pk_bf16_f32 v53, v122, v123
	v_cvt_pk_bf16_f32 v54, v126, v127
	v_cvt_pk_bf16_f32 v55, v130, v131
	v_exp_f32_e32 v33, v33
	v_exp_f32_e32 v34, v34
	v_exp_f32_e32 v35, v35
	s_waitcnt lgkmcnt(0)
	v_mfma_f32_32x32x16_bf16 v[16:31], v[52:55], v[56:59], v[16:31]
	v_add_f32_e32 v44, 0xc26c0000, v133
	v_fma_f32 v60, -v167, |v44|, v47
	v_cvt_pk_bf16_f32 v40, v32, v33
	v_cvt_pk_bf16_f32 v41, v34, v35
	v_cvt_pk_bf16_f32 v42, v112, v113
	v_cvt_pk_bf16_f32 v43, v116, v117
	ds_read_b64_tr_b16 v[44:45], v134 offset:34816
	ds_read_b64_tr_b16 v[46:47], v134 offset:35328
	v_exp_f32_e32 v133, v60
	s_waitcnt lgkmcnt(0)
	v_mfma_f32_32x32x16_bf16 v[16:31], v[40:43], v[44:47], v[16:31]
	v_cvt_pk_bf16_f32 v56, v120, v121
	ds_read_b64_tr_b16 v[60:61], v134 offset:35840
	ds_read_b64_tr_b16 v[62:63], v134 offset:36352
	v_cvt_pk_bf16_f32 v57, v124, v125
	v_cvt_pk_bf16_f32 v58, v128, v129
	v_cvt_pk_bf16_f32 v59, v132, v133
	s_waitcnt lgkmcnt(0)
	s_nop 0
	v_mfma_f32_32x32x16_bf16 v[16:31], v[56:59], v[60:63], v[16:31]
	ds_read_b64_tr_b16 v[44:45], v134 offset:36864
	ds_read_b64_tr_b16 v[46:47], v134 offset:37376
	ds_read_b64_tr_b16 v[60:61], v134 offset:37888
	ds_read_b64_tr_b16 v[62:63], v134 offset:38400
	s_waitcnt lgkmcnt(2)
	v_mfma_f32_32x32x16_bf16 v[0:15], v[36:39], v[44:47], v[0:15]
	v_add_f32_e64 v36, v48, 0
	v_add_f32_e64 v37, v49, 0
	v_add_f32_e64 v32, v32, v36
	v_add_f32_e64 v33, v33, v37
	v_add_f32_e64 v32, v50, v32
	v_add_f32_e64 v33, v51, v33
	v_pk_add_f32 v[32:33], v[34:35], v[32:33]
	s_waitcnt lgkmcnt(0)
	v_mfma_f32_32x32x16_bf16 v[0:15], v[52:55], v[60:63], v[0:15]
	v_add_f32_e64 v32, v110, v32
	v_add_f32_e64 v33, v111, v33
	v_add_f32_e64 v32, v112, v32
	v_add_f32_e64 v33, v113, v33
	v_add_f32_e64 v32, v114, v32
	v_add_f32_e64 v33, v115, v33
	v_pk_add_f32 v[36:37], v[116:117], v[32:33]
	ds_read_b64_tr_b16 v[32:33], v134 offset:38912
	ds_read_b64_tr_b16 v[34:35], v134 offset:39424
	s_waitcnt lgkmcnt(0)
	v_mfma_f32_32x32x16_bf16 v[0:15], v[40:43], v[32:35], v[0:15]
	v_add_f32_e64 v36, v118, v36
	v_add_f32_e64 v37, v119, v37
	v_add_f32_e64 v44, v120, v36
	v_add_f32_e64 v45, v121, v37
	ds_read_b64_tr_b16 v[36:37], v134 offset:39936
	ds_read_b64_tr_b16 v[38:39], v134 offset:40448
	v_pk_add_f32 v[32:33], v[122:123], v[44:45]
	s_nop 0
	v_pk_add_f32 v[32:33], v[124:125], v[32:33]
	s_waitcnt lgkmcnt(0)
	v_mfma_f32_32x32x16_bf16 v[0:15], v[56:59], v[36:39], v[0:15]
	v_add_f32_e64 v32, v126, v32
	v_add_f32_e64 v33, v127, v33
	v_add_f32_e64 v32, v128, v32
	v_add_f32_e64 v33, v129, v33
	v_add_f32_e64 v32, v130, v32
	v_add_f32_e64 v33, v131, v33
	v_pk_add_f32 v[32:33], v[132:133], v[32:33]
	s_nop 0
	v_add_f32_e32 v32, v32, v33
	v_add_f32_e32 v109, v109, v32
	s_branch .LBB0_1359

; template <int TYPE> __device__ __forceinline__ void attn_unit(const AttnCtx& C, int b, int h, int qb, LAS unsigned char* lds, int tid_in, unsigned* counter) {
;     ...
;             const bool active = (TYPE == 2) ? (t >= cq - 8 && t <= cq) : (TYPE == 0) ? (t <= cq && (float)(256 * qb + 32 * w - 64 * t - 63) < dmax) : (t <= cq && t >= tfirst);
;             if (active) {
;                 f32x16 p0, p1;
;                 const LAS unsigned char* kp = Kb + bo + hi * 1024 + r32 * 16;
; #pragma unroll
;                 for (int d0 = 0; d0 < 4; ++d0) {
;                     const bf16x8 a0 = *(const LAS bf16x8*)(kp + d0 * 2048), a1 = *(const LAS bf16x8*)(kp + d0 * 2048 + 512);
;                     if (d0 == 0) { p0 = MFMA32(a0, qr[0], (TYPE == 1 ? cvec : zvec)); p1 = MFMA32(a1, qr[0], (TYPE == 1 ? cvec : zvec)); }
;                     else { p0 = MFMA32(a0, qr[d0], p0); p1 = MFMA32(a1, qr[d0], p1); }
;                 }
;                 const int xi = sq - 64 * t - 4 * hi;
;                 if (TYPE == 0) {
;                     const float xf = (float)xi;
; #pragma unroll
;                     for (int r = 0; r < 16; ++r) { const float c = (float)((r & 3) + 8 * (r >> 2));
;                         p0[r] = fast_exp2(p0[r] - sl2 * fabsf(xf - c)); p1[r] = fast_exp2(p1[r] - sl2 * fabsf(xf - (c + 32.f))); }
;                 } else if (TYPE == 1) {
;                     const LAS float* fp = Fb + (t & 3) * 64 + 4 * hi;
; #pragma unroll
;                     for (int g = 0; g < 4; ++g) { const f32x4 fa = *(const LAS f32x4*)(fp + 8 * g), fb2 = *(const LAS f32x4*)(fp + 32 + 8 * g);
; #pragma unroll
;                         for (int i = 0; i < 4; i += 2) {
;                             const f32x2_t d0_ = (f32x2_t){p0[4 * g + i], p0[4 * g + i + 1]} - (f32x2_t){fa[i], fa[i + 1]}, d1_ = (f32x2_t){p1[4 * g + i], p1[4 * g + i + 1]} - (f32x2_t){fb2[i], fb2[i + 1]};
;                             p0[4 * g + i] = fast_exp2(d0_[0]); p0[4 * g + i + 1] = fast_exp2(d0_[1]); p1[4 * g + i] = fast_exp2(d1_[0]); p1[4 * g + i + 1] = fast_exp2(d1_[1]); } }
;                     if (t == cq) { const int qrel = 32 * (w & 1) + r32;
; #pragma unroll
;                         for (int r = 0; r < 16; ++r) { const int kv = crow(r, hi); if (kv > qrel) p0[r] = 0.f; if (kv + 32 > qrel) p1[r] = 0.f; } }
;                 } else {
;                     if (cq - t >= 3) { const float bc = relb[256];
.LBB0_1380:
	s_cmp_gt_i32 s13, s12
	s_cbranch_scc1 .LBB0_1371
	s_sub_i32 s0, s15, 63
	s_waitcnt vmcnt(15)
	v_cvt_f32_i32_e32 v64, s0
	v_cmp_ngt_f32_e32 vcc, v168, v64
	s_cbranch_vccnz .LBB0_1371
	s_cmp_eq_u32 s13, s12
	s_cbranch_scc1 .Lt0diag_1
	v_add_u32_e32 v184, s17, v171
	v_add_u32_e32 v213, s15, v172
	v_cvt_f32_i32_e32 v213, v213
	v_mul_f32_e64 v210, -v167, v213
	ds_read_b128 v[202:205], v184
	s_waitcnt vmcnt(14)
	ds_read_b128 v[206:209], v184 offset:512
	ds_read_b128 v[176:179], v184 offset:2048
	ds_read_b128 v[180:183], v184 offset:2560
	v_add_u32_e32 v200, s17, v170
	v_mov_b32_e32 v80, v210
	v_fmamk_f32 v81, v167, 0x3f800000, v210
	v_fmamk_f32 v82, v167, 0x40000000, v210
	v_fmamk_f32 v83, v167, 0x40400000, v210
	v_fmamk_f32 v84, v167, 0x41000000, v210
	v_fmamk_f32 v85, v167, 0x41100000, v210
	v_fmamk_f32 v86, v167, 0x41200000, v210
	v_fmamk_f32 v87, v167, 0x41300000, v210
	v_fmamk_f32 v88, v167, 0x41800000, v210
	v_fmamk_f32 v89, v167, 0x41880000, v210
	v_fmamk_f32 v90, v167, 0x41900000, v210
	v_fmamk_f32 v91, v167, 0x41980000, v210
	v_fmamk_f32 v92, v167, 0x41c00000, v210
	v_fmamk_f32 v93, v167, 0x41c80000, v210
	v_fmamk_f32 v94, v167, 0x41d00000, v210
	v_fmamk_f32 v95, v167, 0x41d80000, v210
	v_fmamk_f32 v64, v167, 0x42000000, v210
	v_fmamk_f32 v65, v167, 0x42040000, v210
	v_fmamk_f32 v66, v167, 0x42080000, v210
	v_fmamk_f32 v67, v167, 0x420c0000, v210
	v_fmamk_f32 v68, v167, 0x42200000, v210
	v_fmamk_f32 v69, v167, 0x42240000, v210
	v_fmamk_f32 v70, v167, 0x42280000, v210
	v_fmamk_f32 v71, v167, 0x422c0000, v210
	v_fmamk_f32 v72, v167, 0x42400000, v210
	v_fmamk_f32 v73, v167, 0x42440000, v210
	v_fmamk_f32 v74, v167, 0x42480000, v210
	v_fmamk_f32 v75, v167, 0x424c0000, v210
	v_fmamk_f32 v76, v167, 0x42600000, v210
	v_fmamk_f32 v77, v167, 0x42640000, v210
	v_fmamk_f32 v78, v167, 0x42680000, v210
	v_fmamk_f32 v79, v167, 0x426c0000, v210
	s_waitcnt vmcnt(7) lgkmcnt(3)
	v_mfma_f32_32x32x16_bf16 v[80:95], v[202:205], v[112:115], v[80:95]
	s_waitcnt lgkmcnt(2)
	v_mfma_f32_32x32x16_bf16 v[64:79], v[206:209], v[112:115], v[64:79]
	s_waitcnt vmcnt(6) lgkmcnt(0)
	v_mfma_f32_32x32x16_bf16 v[64:79], v[180:183], v[116:119], v[64:79]
	v_mfma_f32_32x32x16_bf16 v[80:95], v[176:179], v[116:119], v[80:95]
	ds_read_b128 v[176:179], v184 offset:4096
	ds_read_b128 v[180:183], v184 offset:4608
	s_waitcnt vmcnt(5) lgkmcnt(0)
	v_mfma_f32_32x32x16_bf16 v[64:79], v[180:183], v[120:123], v[64:79]
	v_mfma_f32_32x32x16_bf16 v[80:95], v[176:179], v[120:123], v[80:95]
	ds_read_b128 v[176:179], v184 offset:6144
	ds_read_b128 v[180:183], v184 offset:6656
	s_waitcnt vmcnt(4) lgkmcnt(0)
	v_mfma_f32_32x32x16_bf16 v[64:79], v[180:183], v[124:127], v[64:79]
	v_mfma_f32_32x32x16_bf16 v[80:95], v[176:179], v[124:127], v[80:95]
	s_nop 11
	v_exp_f32_e32 v64, v64
	v_exp_f32_e32 v176, v84
	v_exp_f32_e32 v178, v68
	v_exp_f32_e32 v177, v85
	v_exp_f32_e32 v179, v69
	v_exp_f32_e32 v180, v86
	v_exp_f32_e32 v182, v70
	v_exp_f32_e32 v181, v87
	v_exp_f32_e32 v183, v71
	v_exp_f32_e32 v184, v88
	v_exp_f32_e32 v186, v72
	v_exp_f32_e32 v185, v89
	v_exp_f32_e32 v187, v73
	v_exp_f32_e32 v188, v90
	v_exp_f32_e32 v190, v74
	v_exp_f32_e32 v189, v91
	v_exp_f32_e32 v191, v75
	v_exp_f32_e32 v192, v92
	v_exp_f32_e32 v194, v76
	v_exp_f32_e32 v193, v93
	v_exp_f32_e32 v195, v77
	v_exp_f32_e32 v80, v80
	v_exp_f32_e32 v81, v81
	v_exp_f32_e32 v82, v82
	v_exp_f32_e32 v83, v83
	v_exp_f32_e32 v196, v94
	v_exp_f32_e32 v198, v78
	v_exp_f32_e32 v197, v95
	v_cvt_pk_bf16_f32 v68, v80, v81
	v_cvt_pk_bf16_f32 v69, v82, v83
	v_cvt_pk_bf16_f32 v70, v176, v177
	v_cvt_pk_bf16_f32 v71, v180, v181
	ds_read_b64_tr_b16 v[72:73], v200 offset:32768
	ds_read_b64_tr_b16 v[74:75], v200 offset:33280
	s_waitcnt lgkmcnt(0)
	v_mfma_f32_32x32x16_bf16 v[48:63], v[68:71], v[72:75], v[48:63]
	v_cvt_pk_bf16_f32 v84, v184, v185
	ds_read_b64_tr_b16 v[88:89], v200 offset:33792
	ds_read_b64_tr_b16 v[90:91], v200 offset:34304
	v_cvt_pk_bf16_f32 v85, v188, v189
	v_cvt_pk_bf16_f32 v86, v192, v193
	v_cvt_pk_bf16_f32 v87, v196, v197
	v_exp_f32_e32 v65, v65
	v_exp_f32_e32 v66, v66
	v_exp_f32_e32 v67, v67
	s_waitcnt lgkmcnt(0)
	v_mfma_f32_32x32x16_bf16 v[48:63], v[84:87], v[88:91], v[48:63]
	v_exp_f32_e32 v199, v79
	v_cvt_pk_bf16_f32 v72, v64, v65
	v_cvt_pk_bf16_f32 v73, v66, v67
	v_cvt_pk_bf16_f32 v74, v178, v179
	v_cvt_pk_bf16_f32 v75, v182, v183
	ds_read_b64_tr_b16 v[76:77], v200 offset:34816
	ds_read_b64_tr_b16 v[78:79], v200 offset:35328
	s_waitcnt lgkmcnt(0)
	v_mfma_f32_32x32x16_bf16 v[48:63], v[72:75], v[76:79], v[48:63]
	v_cvt_pk_bf16_f32 v88, v186, v187
	ds_read_b64_tr_b16 v[92:93], v200 offset:35840
	ds_read_b64_tr_b16 v[94:95], v200 offset:36352
	v_cvt_pk_bf16_f32 v89, v190, v191
	v_cvt_pk_bf16_f32 v90, v194, v195
	v_cvt_pk_bf16_f32 v91, v198, v199
	s_waitcnt lgkmcnt(0)
	s_nop 0
	v_mfma_f32_32x32x16_bf16 v[48:63], v[88:91], v[92:95], v[48:63]
	ds_read_b64_tr_b16 v[76:77], v200 offset:36864
	ds_read_b64_tr_b16 v[78:79], v200 offset:37376
	ds_read_b64_tr_b16 v[92:93], v200 offset:37888
	ds_read_b64_tr_b16 v[94:95], v200 offset:38400
	s_waitcnt lgkmcnt(2)
	v_mfma_f32_32x32x16_bf16 v[32:47], v[68:71], v[76:79], v[32:47]
	v_add_f32_e64 v68, v80, 0
	v_add_f32_e64 v69, v81, 0
	v_add_f32_e64 v64, v64, v68
	v_add_f32_e64 v65, v65, v69
	v_add_f32_e64 v64, v82, v64
	v_add_f32_e64 v65, v83, v65
	v_pk_add_f32 v[64:65], v[66:67], v[64:65]
	s_waitcnt lgkmcnt(0)
	v_mfma_f32_32x32x16_bf16 v[32:47], v[84:87], v[92:95], v[32:47]
	v_add_f32_e64 v64, v176, v64
	v_add_f32_e64 v65, v177, v65
	v_add_f32_e64 v64, v178, v64
	v_add_f32_e64 v65, v179, v65
	v_add_f32_e64 v64, v180, v64
	v_add_f32_e64 v65, v181, v65
	v_pk_add_f32 v[68:69], v[182:183], v[64:65]
	ds_read_b64_tr_b16 v[64:65], v200 offset:38912
	ds_read_b64_tr_b16 v[66:67], v200 offset:39424
	s_waitcnt lgkmcnt(0)
	v_mfma_f32_32x32x16_bf16 v[32:47], v[72:75], v[64:67], v[32:47]
	v_add_f32_e64 v68, v184, v68
	v_add_f32_e64 v69, v185, v69
	v_add_f32_e64 v76, v186, v68
	v_add_f32_e64 v77, v187, v69
	ds_read_b64_tr_b16 v[68:69], v200 offset:39936
	ds_read_b64_tr_b16 v[70:71], v200 offset:40448
	v_pk_add_f32 v[64:65], v[188:189], v[76:77]
	s_nop 0
	v_pk_add_f32 v[64:65], v[190:191], v[64:65]
	s_waitcnt lgkmcnt(0)
	v_mfma_f32_32x32x16_bf16 v[32:47], v[88:91], v[68:71], v[32:47]
	v_add_f32_e64 v64, v192, v64
	v_add_f32_e64 v65, v193, v65
	v_add_f32_e64 v64, v194, v64
	v_add_f32_e64 v65, v195, v65
	v_add_f32_e64 v64, v196, v64
	v_add_f32_e64 v65, v197, v65
	v_pk_add_f32 v[64:65], v[198:199], v[64:65]
	s_nop 0
	v_add_f32_e32 v64, v64, v65
	v_add_f32_e32 v175, v175, v64
	s_branch .LBB0_1371
; #define LAS __attribute__((address_space(3)))
; __device__ __forceinline__ float fast_exp2(float x) { return __builtin_amdgcn_exp2f(x); }
; #define MFMA32(a, b, c) __builtin_amdgcn_mfma_f32_32x32x16_bf16((a), (b), (c), 0, 0, 0)
; template <int TYPE> __device__ __forceinline__ void attn_unit(const AttnCtx& C, int b, int h, int qb, LAS unsigned char* lds, int tid_in, unsigned* counter) {
;     ...
;                 f32x16 p0, p1;
;                 const LAS unsigned char* kp = Kb + bo + hi * 1024 + r32 * 16;
; #pragma unroll
;                 for (int d0 = 0; d0 < 4; ++d0) {
;                     const bf16x8 a0 = *(const LAS bf16x8*)(kp + d0 * 2048), a1 = *(const LAS bf16x8*)(kp + d0 * 2048 + 512);
;                     if (d0 == 0) { p0 = MFMA32(a0, qr[0], (TYPE == 1 ? cvec : zvec)); p1 = MFMA32(a1, qr[0], (TYPE == 1 ? cvec : zvec)); }
;                     else { p0 = MFMA32(a0, qr[d0], p0); p1 = MFMA32(a1, qr[d0], p1); }
;                 }
;                 const int xi = sq - 64 * t - 4 * hi;
;                 if (TYPE == 0) {
;                     const float xf = (float)xi;
; #pragma unroll
;                     for (int r = 0; r < 16; ++r) { const float c = (float)((r & 3) + 8 * (r >> 2));
;                         p0[r] = fast_exp2(p0[r] - sl2 * fabsf(xf - c)); p1[r] = fast_exp2(p1[r] - sl2 * fabsf(xf - (c + 32.f))); }
.Lt0diag_1:
	v_add_u32_e32 v184, s17, v171
	ds_read_b128 v[64:67], v184
	s_waitcnt vmcnt(14)
	ds_read_b128 v[68:71], v184 offset:512
	ds_read_b128 v[176:179], v184 offset:2048
	ds_read_b128 v[180:183], v184 offset:2560
	v_add_u32_e32 v200, s17, v170
	s_waitcnt vmcnt(7) lgkmcnt(3)
	v_mfma_f32_32x32x16_bf16 v[80:95], v[64:67], v[112:115], 0
	s_waitcnt lgkmcnt(2)
	v_mfma_f32_32x32x16_bf16 v[64:79], v[68:71], v[112:115], 0
	s_waitcnt vmcnt(6) lgkmcnt(0)
	v_mfma_f32_32x32x16_bf16 v[64:79], v[180:183], v[116:119], v[64:79]
	v_mfma_f32_32x32x16_bf16 v[80:95], v[176:179], v[116:119], v[80:95]
	ds_read_b128 v[176:179], v184 offset:4096
	ds_read_b128 v[180:183], v184 offset:4608
	s_waitcnt vmcnt(5) lgkmcnt(0)
	v_mfma_f32_32x32x16_bf16 v[64:79], v[180:183], v[120:123], v[64:79]
	v_mfma_f32_32x32x16_bf16 v[80:95], v[176:179], v[120:123], v[80:95]
	ds_read_b128 v[176:179], v184 offset:6144
	ds_read_b128 v[180:183], v184 offset:6656
	v_add_u32_e32 v184, s15, v172
	v_cvt_f32_i32_e32 v199, v184
	s_waitcnt vmcnt(4) lgkmcnt(0)
	v_mfma_f32_32x32x16_bf16 v[64:79], v[180:183], v[124:127], v[64:79]
	v_mfma_f32_32x32x16_bf16 v[80:95], v[176:179], v[124:127], v[80:95]
	v_add_f32_e32 v176, 0xc2000000, v199
	s_nop 9
	v_fma_f32 v64, -v167, |v176|, v64
	v_add_f32_e32 v176, -1.0, v199
	v_exp_f32_e32 v64, v64
	v_fma_f32 v81, -v167, |v176|, v81
	v_add_f32_e32 v176, 0xc2040000, v199
	v_fma_f32 v65, -v167, |v176|, v65
	v_add_f32_e32 v176, -2.0, v199
	v_fma_f32 v82, -v167, |v176|, v82
	v_add_f32_e32 v176, 0xc2080000, v199
	v_fma_f32 v66, -v167, |v176|, v66
	v_add_f32_e32 v176, 0xc0400000, v199
	v_fma_f32 v83, -v167, |v176|, v83
	v_add_f32_e32 v176, 0xc20c0000, v199
	v_fma_f32 v67, -v167, |v176|, v67
	v_add_f32_e32 v176, 0xc1000000, v199
	v_fma_f32 v84, -v167, |v176|, v84
	v_exp_f32_e32 v176, v84
	v_add_f32_e32 v84, 0xc2200000, v199
	v_fma_f32 v68, -v167, |v84|, v68
	v_exp_f32_e32 v178, v68
	v_add_f32_e32 v68, 0xc1100000, v199
	v_fma_f32 v68, -v167, |v68|, v85
	v_exp_f32_e32 v177, v68
	v_add_f32_e32 v68, 0xc2240000, v199
	v_fma_f32 v68, -v167, |v68|, v69
	v_exp_f32_e32 v179, v68
	v_add_f32_e32 v68, 0xc1200000, v199
	v_fma_f32 v68, -v167, |v68|, v86
	v_exp_f32_e32 v180, v68
	v_add_f32_e32 v68, 0xc2280000, v199
	v_fma_f32 v68, -v167, |v68|, v70
	v_exp_f32_e32 v182, v68
	v_add_f32_e32 v68, 0xc1300000, v199
	v_fma_f32 v68, -v167, |v68|, v87
	v_exp_f32_e32 v181, v68
	v_add_f32_e32 v68, 0xc22c0000, v199
	v_fma_f32 v68, -v167, |v68|, v71
	v_exp_f32_e32 v183, v68
	v_add_f32_e32 v68, 0xc1800000, v199
	v_fma_f32 v68, -v167, |v68|, v88
	v_exp_f32_e32 v184, v68
	v_add_f32_e32 v68, 0xc2400000, v199
	v_fma_f32 v68, -v167, |v68|, v72
	v_exp_f32_e32 v186, v68
	v_add_f32_e32 v68, 0xc1880000, v199
	v_fma_f32 v68, -v167, |v68|, v89
	v_exp_f32_e32 v185, v68
	v_add_f32_e32 v68, 0xc2440000, v199
	v_fma_f32 v68, -v167, |v68|, v73
	v_exp_f32_e32 v187, v68
	v_add_f32_e32 v68, 0xc1900000, v199
	v_fma_f32 v68, -v167, |v68|, v90
	v_exp_f32_e32 v188, v68
	v_add_f32_e32 v68, 0xc2480000, v199
	v_fma_f32 v68, -v167, |v68|, v74
	v_exp_f32_e32 v190, v68
	v_add_f32_e32 v68, 0xc1980000, v199
	v_fma_f32 v68, -v167, |v68|, v91
	v_exp_f32_e32 v189, v68
	v_add_f32_e32 v68, 0xc24c0000, v199
	v_fma_f32 v68, -v167, |v68|, v75
	v_exp_f32_e32 v191, v68
	v_add_f32_e32 v68, 0xc1c00000, v199
	v_fma_f32 v68, -v167, |v68|, v92
	v_exp_f32_e32 v192, v68
	v_add_f32_e32 v68, 0xc2600000, v199
	v_fma_f32 v68, -v167, |v68|, v76
	v_exp_f32_e32 v194, v68
	v_add_f32_e32 v68, 0xc1c80000, v199
	v_fma_f32 v68, -v167, |v68|, v93
	v_exp_f32_e32 v193, v68
	v_add_f32_e32 v68, 0xc2640000, v199
	v_fma_f32 v68, -v167, |v68|, v77
	v_exp_f32_e32 v195, v68
	v_add_f32_e32 v68, 0xc1d00000, v199
	v_fma_f32 v80, -v167, |v199|, v80
	v_fma_f32 v68, -v167, |v68|, v94
	v_exp_f32_e32 v80, v80
	v_exp_f32_e32 v81, v81
	v_exp_f32_e32 v82, v82
	v_exp_f32_e32 v83, v83
	v_exp_f32_e32 v196, v68
	v_add_f32_e32 v68, 0xc2680000, v199
	v_fma_f32 v68, -v167, |v68|, v78
	v_exp_f32_e32 v198, v68
	v_add_f32_e32 v68, 0xc1d80000, v199
	v_fma_f32 v68, -v167, |v68|, v95
	v_exp_f32_e32 v197, v68
	v_cvt_pk_bf16_f32 v68, v80, v81
	v_cvt_pk_bf16_f32 v69, v82, v83
	v_cvt_pk_bf16_f32 v70, v176, v177
	v_cvt_pk_bf16_f32 v71, v180, v181
	ds_read_b64_tr_b16 v[72:73], v200 offset:32768
	ds_read_b64_tr_b16 v[74:75], v200 offset:33280
	s_waitcnt lgkmcnt(0)
; #define LAS __attribute__((address_space(3)))
; __device__ __forceinline__ unsigned pk2(float lo, float hi) { f32x2_t v = {lo, hi}; bf16x2_t b = __builtin_convertvector(v, bf16x2_t); return __builtin_bit_cast(unsigned, b); }
; #define MFMA32(a, b, c) __builtin_amdgcn_mfma_f32_32x32x16_bf16((a), (b), (c), 0, 0, 0)
; __device__ __forceinline__ s16x4 vtr(const LAS unsigned char* p) { return __builtin_bit_cast(s16x4, __builtin_amdgcn_ds_read_tr16_b64_v4i16((LAS v4i16_t*)p)); }
; template <int TYPE> __device__ __forceinline__ void attn_unit(const AttnCtx& C, int b, int h, int qb, LAS unsigned char* lds, int tid_in, unsigned* counter) {
;     ...
;                 f32x2_t a2 = {0.f, 0.f};
; #pragma unroll
;                 for (int r = 0; r < 16; r += 2) { a2 += (f32x2_t){p0[r], p0[r + 1]}; a2 += (f32x2_t){p1[r], p1[r + 1]}; }
;                 lsum += a2[0] + a2[1];
;                 bf16x8 pa[4];
; #pragma unroll
;                 for (int s = 0; s < 2; ++s) {
;                     u32x4 a, c2;
;                     a.x = pk2(p0[8 * s + 0], p0[8 * s + 1]); a.y = pk2(p0[8 * s + 2], p0[8 * s + 3]); a.z = pk2(p0[8 * s + 4], p0[8 * s + 5]); a.w = pk2(p0[8 * s + 6], p0[8 * s + 7]);
;                     c2.x = pk2(p1[8 * s + 0], p1[8 * s + 1]); c2.y = pk2(p1[8 * s + 2], p1[8 * s + 3]); c2.z = pk2(p1[8 * s + 4], p1[8 * s + 5]); c2.w = pk2(p1[8 * s + 6], p1[8 * s + 7]);
;                     pa[s] = __builtin_bit_cast(bf16x8, a); pa[2 + s] = __builtin_bit_cast(bf16x8, c2);
;                 }
;                 const LAS unsigned char* vp = Vb + bo + vb0;
; #pragma unroll
;                 for (int dh = 0; dh < 2; ++dh)
; #pragma unroll
;                     for (int ks = 0; ks < 4; ++ks) {
;                         const s16x4 lo = vtr(vp + dh * 4096 + ks * 1024), hh = vtr(vp + dh * 4096 + ks * 1024 + 512);
;                         const bf16x8 vf = {lo[0], lo[1], lo[2], lo[3], hh[0], hh[1], hh[2], hh[3]};
;                         o[dh] = MFMA32(pa[ks], vf, o[dh]);
;                     }
	v_mfma_f32_32x32x16_bf16 v[48:63], v[68:71], v[72:75], v[48:63]
	v_cvt_pk_bf16_f32 v84, v184, v185
	ds_read_b64_tr_b16 v[88:89], v200 offset:33792
	ds_read_b64_tr_b16 v[90:91], v200 offset:34304
	v_cvt_pk_bf16_f32 v85, v188, v189
	v_cvt_pk_bf16_f32 v86, v192, v193
	v_cvt_pk_bf16_f32 v87, v196, v197
	v_exp_f32_e32 v65, v65
	v_exp_f32_e32 v66, v66
	v_exp_f32_e32 v67, v67
	s_waitcnt lgkmcnt(0)
	v_mfma_f32_32x32x16_bf16 v[48:63], v[84:87], v[88:91], v[48:63]
	v_add_f32_e32 v76, 0xc26c0000, v199
	v_fma_f32 v92, -v167, |v76|, v79
	v_cvt_pk_bf16_f32 v72, v64, v65
	v_cvt_pk_bf16_f32 v73, v66, v67
	v_cvt_pk_bf16_f32 v74, v178, v179
	v_cvt_pk_bf16_f32 v75, v182, v183
	ds_read_b64_tr_b16 v[76:77], v200 offset:34816
	ds_read_b64_tr_b16 v[78:79], v200 offset:35328
	v_exp_f32_e32 v199, v92
	s_waitcnt lgkmcnt(0)
	v_mfma_f32_32x32x16_bf16 v[48:63], v[72:75], v[76:79], v[48:63]
	v_cvt_pk_bf16_f32 v88, v186, v187
	ds_read_b64_tr_b16 v[92:93], v200 offset:35840
	ds_read_b64_tr_b16 v[94:95], v200 offset:36352
	v_cvt_pk_bf16_f32 v89, v190, v191
	v_cvt_pk_bf16_f32 v90, v194, v195
	v_cvt_pk_bf16_f32 v91, v198, v199
	s_waitcnt lgkmcnt(0)
	s_nop 0
	v_mfma_f32_32x32x16_bf16 v[48:63], v[88:91], v[92:95], v[48:63]
	ds_read_b64_tr_b16 v[76:77], v200 offset:36864
	ds_read_b64_tr_b16 v[78:79], v200 offset:37376
	ds_read_b64_tr_b16 v[92:93], v200 offset:37888
	ds_read_b64_tr_b16 v[94:95], v200 offset:38400
	s_waitcnt lgkmcnt(2)
	v_mfma_f32_32x32x16_bf16 v[32:47], v[68:71], v[76:79], v[32:47]
	v_add_f32_e64 v68, v80, 0
	v_add_f32_e64 v69, v81, 0
	v_add_f32_e64 v64, v64, v68
	v_add_f32_e64 v65, v65, v69
	v_add_f32_e64 v64, v82, v64
	v_add_f32_e64 v65, v83, v65
	v_pk_add_f32 v[64:65], v[66:67], v[64:65]
	s_waitcnt lgkmcnt(0)
	v_mfma_f32_32x32x16_bf16 v[32:47], v[84:87], v[92:95], v[32:47]
	v_add_f32_e64 v64, v176, v64
	v_add_f32_e64 v65, v177, v65
	v_add_f32_e64 v64, v178, v64
	v_add_f32_e64 v65, v179, v65
	v_add_f32_e64 v64, v180, v64
	v_add_f32_e64 v65, v181, v65
	v_pk_add_f32 v[68:69], v[182:183], v[64:65]
	ds_read_b64_tr_b16 v[64:65], v200 offset:38912
	ds_read_b64_tr_b16 v[66:67], v200 offset:39424
	s_waitcnt lgkmcnt(0)
	v_mfma_f32_32x32x16_bf16 v[32:47], v[72:75], v[64:67], v[32:47]
	v_add_f32_e64 v68, v184, v68
	v_add_f32_e64 v69, v185, v69
	v_add_f32_e64 v76, v186, v68
	v_add_f32_e64 v77, v187, v69
	ds_read_b64_tr_b16 v[68:69], v200 offset:39936
	ds_read_b64_tr_b16 v[70:71], v200 offset:40448
	v_pk_add_f32 v[64:65], v[188:189], v[76:77]
	s_nop 0
	v_pk_add_f32 v[64:65], v[190:191], v[64:65]
	s_waitcnt lgkmcnt(0)
	v_mfma_f32_32x32x16_bf16 v[32:47], v[88:91], v[68:71], v[32:47]
	v_add_f32_e64 v64, v192, v64
	v_add_f32_e64 v65, v193, v65
	v_add_f32_e64 v64, v194, v64
	v_add_f32_e64 v65, v195, v65
	v_add_f32_e64 v64, v196, v64
	v_add_f32_e64 v65, v197, v65
	v_pk_add_f32 v[64:65], v[198:199], v[64:65]
	s_nop 0
	v_add_f32_e32 v64, v64, v65
	v_add_f32_e32 v175, v175, v64
	s_branch .LBB0_1371

; __device__ __forceinline__ void xcd_barrier(const XcdBarrier& b, const bool xb_is_leader) {
;     asm volatile("s_waitcnt vmcnt(0)" ::: "memory");
;     __syncthreads();
;     if (xb_is_leader) {
;         unsigned* bar = b.bar;
;         __builtin_amdgcn_s_waitcnt(0);
;         unsigned nloc = b.st[0], nx = b.st[1];
;         if (nloc == 0u) { xcd_barrier_complete(bar, b.x, nloc, nx); b.st[0] = nloc; b.st[1] = nx; }
.LBB0_1388:
	s_mov_b32 s0, -1
	v_readlane_b32 s84, v251, 26
	v_mbcnt_lo_u32_b32 v0, s0, 0
	v_mbcnt_hi_u32_b32 v0, s0, v0
	s_setprio 0
	s_waitcnt vmcnt(0)
	s_waitcnt lgkmcnt(0)
	v_or_b32_e32 v0, s84, v0
	v_cmp_eq_u32_e32 vcc, 0, v0
	s_barrier
	s_and_saveexec_b64 s[4:5], vcc
	v_readlane_b32 s88, v251, 37
	v_readlane_b32 s62, v251, 5
	v_readlane_b32 s85, v251, 27
	v_readlane_b32 s89, v251, 38
	v_readlane_b32 s90, v251, 28
	v_readlane_b32 s91, v251, 3
	v_readlane_b32 s63, v251, 6
	s_cbranch_execz .LBB0_1440
	v_mov_b32_e32 v0, 0x22000
	s_waitcnt vmcnt(0) expcnt(0) lgkmcnt(0)
	ds_read_b32 v2, v0
	v_mov_b32_e32 v0, 0x22004
	ds_read_b32 v0, v0
	s_waitcnt lgkmcnt(1)
	v_cmp_ne_u32_e32 vcc, 0, v2
	s_cbranch_vccnz .LBB0_1404
	v_readlane_b32 s0, v251, 0
	v_readlane_b32 s1, v251, 1
	v_readlane_b32 s2, v251, 2
	s_mul_i32 s2, s1, s2
	s_mul_i32 s2, s2, s0
	s_add_u32 s0, s76, 0x1000
	s_addc_u32 s1, s77, 0
	s_add_u32 s6, s76, 0x1100
	s_addc_u32 s7, s77, 0
	s_add_u32 s8, s76, 0x1200
	s_addc_u32 s9, s77, 0
	s_add_u32 s10, s76, 0x1300
	s_addc_u32 s11, s77, 0
	s_mov_b32 s3, 1
	v_mov_b32_e32 v16, 0
	s_branch .LBB0_1392

; __device__ __forceinline__ unsigned xb_ld(unsigned* p)              { return __hip_atomic_load(p, __ATOMIC_RELAXED, __HIP_MEMORY_SCOPE_AGENT); }
; __device__ __forceinline__ unsigned xb_add(unsigned* p, unsigned v) { return __hip_atomic_fetch_add(p, v, __ATOMIC_RELAXED, __HIP_MEMORY_SCOPE_AGENT); }
; #define XB_SPIN(cond, bar) do { unsigned _sp = 0; while (cond) { __builtin_amdgcn_s_sleep(1); \
;     if ((++_sp & 255u) == 0u) { if (xb_ld(&(bar)[XB_TMO])) break; if (_sp > XB_SPIN_CAP) { atomicAdd(&(bar)[XB_TMO], 1u); break; } } } } while (0)
; #define GSYNC() do { xcd_barrier(xbar, K_TID == 0); xcd_barrier(xbar, K_TID == 0); } while (0)
; #define GSYNC() xcd_barrier(xbar, K_TID == 0)
; __device__ __forceinline__ void xcd_barrier(const XcdBarrier& b, const bool xb_is_leader) {
;     asm volatile("s_waitcnt vmcnt(0)" ::: "memory");
;     __syncthreads();
;     if (xb_is_leader) {
;         unsigned* bar = b.bar;
;         __builtin_amdgcn_s_waitcnt(0);
;         unsigned nloc = b.st[0], nx = b.st[1];
;         if (nloc == 0u) { xcd_barrier_complete(bar, b.x, nloc, nx); b.st[0] = nloc; b.st[1] = nx; }
;         const unsigned old = xb_add(&bar[XB_XSUB(b.x)], 1u);
;         const unsigned gen = old / nloc;
;         if (old + 1u == (gen + 1u) * nloc) {
;             __builtin_amdgcn_fence(__ATOMIC_RELEASE, "agent");
;             asm volatile("s_waitcnt vmcnt(0)" ::: "memory");
;             const unsigned og = xb_add(&bar[XB_TOP], 1u);
;             const unsigned tg = og / nx;
;             if (og + 1u == (tg + 1u) * nx) xb_add(&bar[XB_TOPGEN], 1u);
;             else XB_SPIN(xb_ld(&bar[XB_TOPGEN]) == tg, bar);
;             __builtin_amdgcn_fence(__ATOMIC_ACQUIRE, "agent");
;             xb_add(&bar[XB_XGEN(b.x)], 1u);
;             asm volatile("s_waitcnt vmcnt(0)" ::: "memory");
;         } else {
;             XB_SPIN(xb_ld(&bar[XB_XGEN(b.x)]) == gen, bar);
;             __builtin_amdgcn_fence(__ATOMIC_ACQUIRE, "agent");
;             asm volatile("s_waitcnt vmcnt(0)" ::: "memory");
;         }
;     }
;     __syncthreads();
; __global__ void __launch_bounds__(512, 2) fwd_megakernel(Args a) {
;     ...
;             GSYNC();
.LBB0_1834:
	s_nop 0
	v_mbcnt_lo_u32_b32 v0, s2, 0
	v_mbcnt_hi_u32_b32 v0, s2, v0
	s_waitcnt vmcnt(0)
	s_nop 0
	v_or_b32_e32 v0, s84, v0
	v_cmp_eq_u32_e32 vcc, 0, v0
	s_mov_b64 vcc, 0
	s_barrier
	s_and_saveexec_b64 s[4:5], vcc
	s_cbranch_execz .LBB0_1886
	v_mov_b32_e32 v0, 0x22000
	s_waitcnt vmcnt(0) expcnt(0) lgkmcnt(0)
	ds_read_b32 v2, v0
	v_mov_b32_e32 v0, 0x22004
	ds_read_b32 v0, v0
	s_waitcnt lgkmcnt(1)
	v_cmp_ne_u32_e32 vcc, 0, v2
	s_cbranch_vccnz .LBB0_1850
	v_readlane_b32 s0, v251, 0
	v_readlane_b32 s1, v251, 1
	v_readlane_b32 s2, v251, 2
	s_mul_i32 s2, s1, s2
	s_mul_i32 s2, s2, s0
	s_add_u32 s0, s76, 0x1000
	s_addc_u32 s1, s77, 0
	s_add_u32 s6, s76, 0x1100
	s_addc_u32 s7, s77, 0
	s_add_u32 s10, s76, 0x1200
	s_addc_u32 s11, s77, 0
	s_add_u32 s12, s76, 0x1300
	s_addc_u32 s13, s77, 0
	s_mov_b32 s3, 1
	v_mov_b32_e32 v16, 0
	s_branch .LBB0_1838

; __global__ void __launch_bounds__(512, 2) fwd_megakernel(Args a) {
;     __shared__ __attribute__((aligned(16))) unsigned char lds_raw[LDS_TOTAL];
	.amdhsa_kernel _Z14fwd_megakernel4Args
		.amdhsa_group_segment_fixed_size 149760
		.amdhsa_private_segment_fixed_size 0
		.amdhsa_kernarg_size 416
		.amdhsa_user_sgpr_count 2
		.amdhsa_user_sgpr_dispatch_ptr 0
		.amdhsa_user_sgpr_queue_ptr 0
		.amdhsa_user_sgpr_kernarg_segment_ptr 1
		.amdhsa_user_sgpr_dispatch_id 0
		.amdhsa_user_sgpr_kernarg_preload_length 0
		.amdhsa_user_sgpr_kernarg_preload_offset 0
		.amdhsa_user_sgpr_private_segment_size 0
		.amdhsa_uses_dynamic_stack 0
		.amdhsa_enable_private_segment 0
		.amdhsa_system_sgpr_workgroup_id_x 1
		.amdhsa_system_sgpr_workgroup_id_y 0
		.amdhsa_system_sgpr_workgroup_id_z 0
		.amdhsa_system_sgpr_workgroup_info 0
		.amdhsa_system_vgpr_workitem_id 2
		.amdhsa_next_free_vgpr 252
		.amdhsa_next_free_sgpr 102
		.amdhsa_accum_offset 252
		.amdhsa_reserve_vcc 1
		.amdhsa_float_round_mode_32 0
		.amdhsa_float_round_mode_16_64 0
		.amdhsa_float_denorm_mode_32 3
		.amdhsa_float_denorm_mode_16_64 3
		.amdhsa_dx10_clamp 1
		.amdhsa_ieee_mode 1
		.amdhsa_fp16_overflow 0
		.amdhsa_tg_split 0
		.amdhsa_exception_fp_ieee_invalid_op 0
		.amdhsa_exception_fp_denorm_src 0
		.amdhsa_exception_fp_ieee_div_zero 0
		.amdhsa_exception_fp_ieee_overflow 0
		.amdhsa_exception_fp_ieee_underflow 0
		.amdhsa_exception_fp_ieee_inexact 0
		.amdhsa_exception_int_div_zero 0
	.end_amdhsa_kernel

; __global__ void __launch_bounds__(512, 2) fwd_megakernel(Args a) {
;     __shared__ __attribute__((aligned(16))) unsigned char lds_raw[LDS_TOTAL];
amdhsa.kernels:
  - .agpr_count:     0
    .args:
      - .offset:         0
        .size:           160
        .value_kind:     by_value
      - .offset:         160
        .size:           4
        .value_kind:     hidden_block_count_x
      - .offset:         164
        .size:           4
        .value_kind:     hidden_block_count_y
      - .offset:         168
        .size:           4
        .value_kind:     hidden_block_count_z
      - .offset:         172
        .size:           2
        .value_kind:     hidden_group_size_x
      - .offset:         174
        .size:           2
        .value_kind:     hidden_group_size_y
      - .offset:         176
        .size:           2
        .value_kind:     hidden_group_size_z
      - .offset:         178
        .size:           2
        .value_kind:     hidden_remainder_x
      - .offset:         180
        .size:           2
        .value_kind:     hidden_remainder_y
      - .offset:         182
        .size:           2
        .value_kind:     hidden_remainder_z
      - .offset:         200
        .size:           8
        .value_kind:     hidden_global_offset_x
      - .offset:         208
        .size:           8
        .value_kind:     hidden_global_offset_y
      - .offset:         216
        .size:           8
        .value_kind:     hidden_global_offset_z
      - .offset:         224
        .size:           2
        .value_kind:     hidden_grid_dims
      - .offset:         248
        .size:           8
        .value_kind:     hidden_multigrid_sync_arg
    .group_segment_fixed_size: 149760
    .kernarg_segment_align: 8
    .kernarg_segment_size: 416
    .language:       OpenCL C
    .language_version:
      - 2
      - 0
    .max_flat_workgroup_size: 512
    .name:           _Z14fwd_megakernel4Args
    .private_segment_fixed_size: 0
    .sgpr_count:     108
    .sgpr_spill_count: 61
    .symbol:         _Z14fwd_megakernel4Args.kd
    .uniform_work_group_size: 1
    .uses_dynamic_stack: false
    .vgpr_count:     252
    .vgpr_spill_count: 0
    .wavefront_size: 64
